# cache policy: non-temporal stores for the FFN intermediate a2 (written once, read once by the down GEMM) so it does not displace the residual stream from the memory-side cache
# speedup vs baseline: 1.0073x; 1.0073x over previous
; __device__ __forceinline__ unsigned cvt_pk_bf16(float lo, float hi) { unsigned r; asm volatile("v_cvt_pk_bf16_f32 %0, %1, %2" : "=v"(r) : "v"(lo), "v"(hi)); return r; }
;     __device__ __forceinline__ void operator()(const f32x4 (&acc)[2][2][4][2], const Unit& u, int wr, int wc, int fr_in, int fq_in) const {
;     ...
;                 const int ch = ch0 + 4 * n;
; #pragma unroll
;                 for (int pass = 0; pass < 2; ++pass) {
;                     const int co = pass ? DFF : 0;
;                     const f32x4 k0 = *(const f32x4*)(fk + co + ch), k1 = *(const f32x4*)(fk + DFF2 + co + ch), k2 = *(const f32x4*)(fk + 2 * DFF2 + co + ch), bb = *(const f32x4*)(fb + co + ch);
;                     f32x4 up_prev = (f32x4){0.f, 0.f, 0.f, 0.f}, up_cur, dn_cur, dn_next;
; #pragma unroll
;                     for (int j = 0; j < 4; ++j) dn_cur[j] = DPP_DN(acc[ai][pass][0][n][j]);
; #pragma unroll
;                     for (int m = 0; m < 4; ++m) {
;                         const f32x4 xv = acc[ai][pass][m][n];
; #pragma unroll
;                         for (int j = 0; j < 4; ++j) { up_cur[j] = DPP_UP(xv[j]); dn_next[j] = (m < 3) ? DPP_DN(acc[ai][pass][m < 3 ? m + 1 : 3][n][j]) : 0.f; }
;                         const f32x4 xp = f0 ? up_prev : up_cur, xn = f15 ? dn_next : dn_cur;
;                         const f32x4 c = (k0 * xp + k1 * xv) + (k2 * xn + bb);
;                         if (pass == 0) o[m] = c;
;                         else { f32x4 e;
; #pragma unroll
;                             for (int j = 0; j < 4; ++j) e[j] = __builtin_amdgcn_rcpf(1.0f + __builtin_amdgcn_exp2f(c[j] * -1.4426950408889634f));
;                             o[m] = o[m] * (c * e); }
;                         up_prev = up_cur; dn_cur = dn_next; }
;     ...
;                 if (fr < 2 || fr >= 14) { const int k = fr < 2 ? fr : fr - 12;
;                     const f32x4 xv = fr < 2 ? acc[ai][0][0][n] : acc[ai][0][3][n], yv = fr < 2 ? acc[ai][1][0][n] : acc[ai][1][3][n];
;                     char* sp = sbase + (size_t)((2 * ai + wr) * 4 + k) * (DFF2 * 2) + (size_t)ch * 2;
;                     u32x2 a, b; a.x = cvt_pk_bf16(xv[0], xv[1]); a.y = cvt_pk_bf16(xv[2], xv[3]); b.x = cvt_pk_bf16(yv[0], yv[1]); b.y = cvt_pk_bf16(yv[2], yv[3]);
;                     *(u32x2*)sp = a; *(u32x2*)(sp + DFF * 2) = b; }
.Lp7_nowait:
	ds_read_b128 v[130:133], v213 offset:0
	ds_read_b128 v[134:137], v213 offset:64
	ds_read_b128 v[138:141], v213 offset:128
	ds_read_b128 v[142:145], v213 offset:192
	ds_read_b128 v[158:161], v213 offset:256
	ds_read_b128 v[162:165], v213 offset:320
	ds_read_b128 v[166:169], v213 offset:384
	ds_read_b128 v[170:173], v213 offset:448
	v_cndmask_b32_e64 v202, v106, v110, s[12:13]
	v_cndmask_b32_e64 v203, v107, v111, s[12:13]
	v_cndmask_b32_e64 v204, v108, v112, s[12:13]
	v_cndmask_b32_e64 v205, v109, v113, s[12:13]
	v_cndmask_b32_e64 v206, v98, v102, s[12:13]
	v_cndmask_b32_e64 v207, v99, v103, s[12:13]
	v_cndmask_b32_e64 v208, v100, v104, s[12:13]
	v_cndmask_b32_e64 v209, v101, v105, s[12:13]
	v_cvt_pk_bf16_f32 v250, v202, v203
	v_cvt_pk_bf16_f32 v251, v204, v205
	v_cvt_pk_bf16_f32 v252, v206, v207
	v_cvt_pk_bf16_f32 v253, v208, v209
	s_mov_b64 s[42:43], exec
	s_and_b64 exec, exec, s[22:23]
	global_store_dwordx2 v195, v[250:251], s[10:11]
	global_store_dwordx2 v197, v[252:253], s[10:11]
	s_mov_b64 exec, s[42:43]
	s_waitcnt lgkmcnt(0)
	v_fma_f32 v174, v134, v110, v142
	v_fma_f32 v175, v135, v111, v143
	v_fma_f32 v176, v136, v112, v144
	v_fma_f32 v177, v137, v113, v145
	v_fma_f32 v178, v134, v126, v142
	v_fma_f32 v179, v135, v127, v143
	v_fma_f32 v180, v136, v128, v144
	v_fma_f32 v181, v137, v129, v145
	v_fma_f32 v186, v134, v122, v142
	v_fma_f32 v187, v135, v123, v143
	v_fma_f32 v188, v136, v124, v144
	v_fma_f32 v189, v137, v125, v145
	v_fma_f32 v190, v134, v106, v142
	v_fma_f32 v191, v135, v107, v143
	v_fma_f32 v192, v136, v108, v144
	v_fma_f32 v193, v137, v109, v145
	v_fmac_f32_dpp v174, v110, v130 row_shr:1 row_mask:0xf bank_mask:0xf
	v_fmac_f32_dpp v175, v111, v131 row_shr:1 row_mask:0xf bank_mask:0xf
	v_fmac_f32_dpp v176, v112, v132 row_shr:1 row_mask:0xf bank_mask:0xf
	v_fmac_f32_dpp v177, v113, v133 row_shr:1 row_mask:0xf bank_mask:0xf
	v_fmac_f32_dpp v174, v110, v138 row_shl:1 row_mask:0xf bank_mask:0xf
	v_fmac_f32_dpp v175, v111, v139 row_shl:1 row_mask:0xf bank_mask:0xf
	v_fmac_f32_dpp v176, v112, v140 row_shl:1 row_mask:0xf bank_mask:0xf
	v_fmac_f32_dpp v177, v113, v141 row_shl:1 row_mask:0xf bank_mask:0xf
	v_fmac_f32_dpp v174, v126, v138 row_shr:15 row_mask:0xf bank_mask:0xf
	v_fmac_f32_dpp v175, v127, v139 row_shr:15 row_mask:0xf bank_mask:0xf
	v_fmac_f32_dpp v176, v128, v140 row_shr:15 row_mask:0xf bank_mask:0xf
	v_fmac_f32_dpp v177, v129, v141 row_shr:15 row_mask:0xf bank_mask:0xf
	v_fmac_f32_dpp v178, v126, v130 row_shr:1 row_mask:0xf bank_mask:0xf
	v_fmac_f32_dpp v179, v127, v131 row_shr:1 row_mask:0xf bank_mask:0xf
	v_fmac_f32_dpp v180, v128, v132 row_shr:1 row_mask:0xf bank_mask:0xf
	v_fmac_f32_dpp v181, v129, v133 row_shr:1 row_mask:0xf bank_mask:0xf
	v_fmac_f32_dpp v178, v110, v130 row_shl:15 row_mask:0xf bank_mask:0xf
	v_fmac_f32_dpp v179, v111, v131 row_shl:15 row_mask:0xf bank_mask:0xf
	v_fmac_f32_dpp v180, v112, v132 row_shl:15 row_mask:0xf bank_mask:0xf
	v_fmac_f32_dpp v181, v113, v133 row_shl:15 row_mask:0xf bank_mask:0xf
	v_fmac_f32_dpp v178, v126, v138 row_shl:1 row_mask:0xf bank_mask:0xf
	v_fmac_f32_dpp v179, v127, v139 row_shl:1 row_mask:0xf bank_mask:0xf
	v_fmac_f32_dpp v180, v128, v140 row_shl:1 row_mask:0xf bank_mask:0xf
	v_fmac_f32_dpp v181, v129, v141 row_shl:1 row_mask:0xf bank_mask:0xf
	v_fmac_f32_dpp v178, v122, v138 row_shr:15 row_mask:0xf bank_mask:0xf
	v_fmac_f32_dpp v179, v123, v139 row_shr:15 row_mask:0xf bank_mask:0xf
	v_fmac_f32_dpp v180, v124, v140 row_shr:15 row_mask:0xf bank_mask:0xf
	v_fmac_f32_dpp v181, v125, v141 row_shr:15 row_mask:0xf bank_mask:0xf
	v_fmac_f32_dpp v186, v122, v130 row_shr:1 row_mask:0xf bank_mask:0xf
	v_fmac_f32_dpp v187, v123, v131 row_shr:1 row_mask:0xf bank_mask:0xf
	v_fmac_f32_dpp v188, v124, v132 row_shr:1 row_mask:0xf bank_mask:0xf
	v_fmac_f32_dpp v189, v125, v133 row_shr:1 row_mask:0xf bank_mask:0xf
	v_fmac_f32_dpp v186, v126, v130 row_shl:15 row_mask:0xf bank_mask:0xf
	v_fmac_f32_dpp v187, v127, v131 row_shl:15 row_mask:0xf bank_mask:0xf
	v_fmac_f32_dpp v188, v128, v132 row_shl:15 row_mask:0xf bank_mask:0xf
	v_fmac_f32_dpp v189, v129, v133 row_shl:15 row_mask:0xf bank_mask:0xf
	v_fmac_f32_dpp v186, v122, v138 row_shl:1 row_mask:0xf bank_mask:0xf
	v_fmac_f32_dpp v187, v123, v139 row_shl:1 row_mask:0xf bank_mask:0xf
	v_fmac_f32_dpp v188, v124, v140 row_shl:1 row_mask:0xf bank_mask:0xf
	v_fmac_f32_dpp v189, v125, v141 row_shl:1 row_mask:0xf bank_mask:0xf
	v_fmac_f32_dpp v186, v106, v138 row_shr:15 row_mask:0xf bank_mask:0xf
	v_fmac_f32_dpp v187, v107, v139 row_shr:15 row_mask:0xf bank_mask:0xf
	v_fmac_f32_dpp v188, v108, v140 row_shr:15 row_mask:0xf bank_mask:0xf
	v_fmac_f32_dpp v189, v109, v141 row_shr:15 row_mask:0xf bank_mask:0xf
	v_fmac_f32_dpp v190, v106, v130 row_shr:1 row_mask:0xf bank_mask:0xf
	v_fmac_f32_dpp v191, v107, v131 row_shr:1 row_mask:0xf bank_mask:0xf
	v_fmac_f32_dpp v192, v108, v132 row_shr:1 row_mask:0xf bank_mask:0xf
	v_fmac_f32_dpp v193, v109, v133 row_shr:1 row_mask:0xf bank_mask:0xf
	v_fmac_f32_dpp v190, v122, v130 row_shl:15 row_mask:0xf bank_mask:0xf
	v_fmac_f32_dpp v191, v123, v131 row_shl:15 row_mask:0xf bank_mask:0xf
	v_fmac_f32_dpp v192, v124, v132 row_shl:15 row_mask:0xf bank_mask:0xf
	v_fmac_f32_dpp v193, v125, v133 row_shl:15 row_mask:0xf bank_mask:0xf
	v_fmac_f32_dpp v190, v106, v138 row_shl:1 row_mask:0xf bank_mask:0xf
	v_fmac_f32_dpp v191, v107, v139 row_shl:1 row_mask:0xf bank_mask:0xf
	v_fmac_f32_dpp v192, v108, v140 row_shl:1 row_mask:0xf bank_mask:0xf
	v_fmac_f32_dpp v193, v109, v141 row_shl:1 row_mask:0xf bank_mask:0xf
	v_fma_f32 v226, v162, v102, v170
	v_fma_f32 v227, v163, v103, v171
	v_fma_f32 v228, v164, v104, v172
; #define DPP_UP(v) __int_as_float(__builtin_amdgcn_update_dpp(0, __float_as_int(v), 0x121, 0xf, 0xf, false))
; #define DPP_DN(v) __int_as_float(__builtin_amdgcn_update_dpp(0, __float_as_int(v), 0x12F, 0xf, 0xf, false))
;     __device__ __forceinline__ void operator()(const f32x4 (&acc)[2][2][4][2], const Unit& u, int wr, int wc, int fr_in, int fq_in) const {
;     ...
;                     const f32x4 k0 = *(const f32x4*)(fk + co + ch), k1 = *(const f32x4*)(fk + DFF2 + co + ch), k2 = *(const f32x4*)(fk + 2 * DFF2 + co + ch), bb = *(const f32x4*)(fb + co + ch);
;                     f32x4 up_prev = (f32x4){0.f, 0.f, 0.f, 0.f}, up_cur, dn_cur, dn_next;
; #pragma unroll
;                     for (int j = 0; j < 4; ++j) dn_cur[j] = DPP_DN(acc[ai][pass][0][n][j]);
; #pragma unroll
;                     for (int m = 0; m < 4; ++m) {
;                         const f32x4 xv = acc[ai][pass][m][n];
; #pragma unroll
;                         for (int j = 0; j < 4; ++j) { up_cur[j] = DPP_UP(xv[j]); dn_next[j] = (m < 3) ? DPP_DN(acc[ai][pass][m < 3 ? m + 1 : 3][n][j]) : 0.f; }
;                         const f32x4 xp = f0 ? up_prev : up_cur, xn = f15 ? dn_next : dn_cur;
;                         const f32x4 c = (k0 * xp + k1 * xv) + (k2 * xn + bb);
;                         if (pass == 0) o[m] = c;
;                         else { f32x4 e;
; #pragma unroll
;                             for (int j = 0; j < 4; ++j) e[j] = __builtin_amdgcn_rcpf(1.0f + __builtin_amdgcn_exp2f(c[j] * -1.4426950408889634f));
;                             o[m] = o[m] * (c * e); }
;                         up_prev = up_cur; dn_cur = dn_next; }
	v_fma_f32 v229, v165, v105, v173
	v_fma_f32 v230, v162, v118, v170
	v_fma_f32 v231, v163, v119, v171
	v_fma_f32 v232, v164, v120, v172
	v_fma_f32 v233, v165, v121, v173
	v_fma_f32 v234, v162, v114, v170
	v_fma_f32 v235, v163, v115, v171
	v_fma_f32 v236, v164, v116, v172
	v_fma_f32 v237, v165, v117, v173
	v_fma_f32 v238, v162, v98, v170
	v_fma_f32 v239, v163, v99, v171
	v_fma_f32 v240, v164, v100, v172
	v_fma_f32 v241, v165, v101, v173
	v_fmac_f32_dpp v226, v102, v158 row_shr:1 row_mask:0xf bank_mask:0xf
	v_fmac_f32_dpp v227, v103, v159 row_shr:1 row_mask:0xf bank_mask:0xf
	v_fmac_f32_dpp v228, v104, v160 row_shr:1 row_mask:0xf bank_mask:0xf
	v_fmac_f32_dpp v229, v105, v161 row_shr:1 row_mask:0xf bank_mask:0xf
	v_fmac_f32_dpp v226, v102, v166 row_shl:1 row_mask:0xf bank_mask:0xf
	v_fmac_f32_dpp v227, v103, v167 row_shl:1 row_mask:0xf bank_mask:0xf
	v_fmac_f32_dpp v228, v104, v168 row_shl:1 row_mask:0xf bank_mask:0xf
	v_fmac_f32_dpp v229, v105, v169 row_shl:1 row_mask:0xf bank_mask:0xf
	v_fmac_f32_dpp v226, v118, v166 row_shr:15 row_mask:0xf bank_mask:0xf
	v_fmac_f32_dpp v227, v119, v167 row_shr:15 row_mask:0xf bank_mask:0xf
	v_fmac_f32_dpp v228, v120, v168 row_shr:15 row_mask:0xf bank_mask:0xf
	v_fmac_f32_dpp v229, v121, v169 row_shr:15 row_mask:0xf bank_mask:0xf
	v_fmac_f32_dpp v230, v118, v158 row_shr:1 row_mask:0xf bank_mask:0xf
	v_fmac_f32_dpp v231, v119, v159 row_shr:1 row_mask:0xf bank_mask:0xf
	v_fmac_f32_dpp v232, v120, v160 row_shr:1 row_mask:0xf bank_mask:0xf
	v_fmac_f32_dpp v233, v121, v161 row_shr:1 row_mask:0xf bank_mask:0xf
	v_fmac_f32_dpp v230, v102, v158 row_shl:15 row_mask:0xf bank_mask:0xf
	v_fmac_f32_dpp v231, v103, v159 row_shl:15 row_mask:0xf bank_mask:0xf
	v_fmac_f32_dpp v232, v104, v160 row_shl:15 row_mask:0xf bank_mask:0xf
	v_fmac_f32_dpp v233, v105, v161 row_shl:15 row_mask:0xf bank_mask:0xf
	v_fmac_f32_dpp v230, v118, v166 row_shl:1 row_mask:0xf bank_mask:0xf
	v_fmac_f32_dpp v231, v119, v167 row_shl:1 row_mask:0xf bank_mask:0xf
	v_fmac_f32_dpp v232, v120, v168 row_shl:1 row_mask:0xf bank_mask:0xf
	v_fmac_f32_dpp v233, v121, v169 row_shl:1 row_mask:0xf bank_mask:0xf
	v_fmac_f32_dpp v230, v114, v166 row_shr:15 row_mask:0xf bank_mask:0xf
	v_fmac_f32_dpp v231, v115, v167 row_shr:15 row_mask:0xf bank_mask:0xf
	v_fmac_f32_dpp v232, v116, v168 row_shr:15 row_mask:0xf bank_mask:0xf
	v_fmac_f32_dpp v233, v117, v169 row_shr:15 row_mask:0xf bank_mask:0xf
	v_fmac_f32_dpp v234, v114, v158 row_shr:1 row_mask:0xf bank_mask:0xf
	v_fmac_f32_dpp v235, v115, v159 row_shr:1 row_mask:0xf bank_mask:0xf
	v_fmac_f32_dpp v236, v116, v160 row_shr:1 row_mask:0xf bank_mask:0xf
	v_fmac_f32_dpp v237, v117, v161 row_shr:1 row_mask:0xf bank_mask:0xf
	v_fmac_f32_dpp v234, v118, v158 row_shl:15 row_mask:0xf bank_mask:0xf
	v_fmac_f32_dpp v235, v119, v159 row_shl:15 row_mask:0xf bank_mask:0xf
	v_fmac_f32_dpp v236, v120, v160 row_shl:15 row_mask:0xf bank_mask:0xf
	v_fmac_f32_dpp v237, v121, v161 row_shl:15 row_mask:0xf bank_mask:0xf
	v_fmac_f32_dpp v234, v114, v166 row_shl:1 row_mask:0xf bank_mask:0xf
	v_fmac_f32_dpp v235, v115, v167 row_shl:1 row_mask:0xf bank_mask:0xf
	v_fmac_f32_dpp v236, v116, v168 row_shl:1 row_mask:0xf bank_mask:0xf
	v_fmac_f32_dpp v237, v117, v169 row_shl:1 row_mask:0xf bank_mask:0xf
	v_fmac_f32_dpp v234, v98, v166 row_shr:15 row_mask:0xf bank_mask:0xf
	v_fmac_f32_dpp v235, v99, v167 row_shr:15 row_mask:0xf bank_mask:0xf
	v_fmac_f32_dpp v236, v100, v168 row_shr:15 row_mask:0xf bank_mask:0xf
	v_fmac_f32_dpp v237, v101, v169 row_shr:15 row_mask:0xf bank_mask:0xf
	v_fmac_f32_dpp v238, v98, v158 row_shr:1 row_mask:0xf bank_mask:0xf
	v_fmac_f32_dpp v239, v99, v159 row_shr:1 row_mask:0xf bank_mask:0xf
	v_fmac_f32_dpp v240, v100, v160 row_shr:1 row_mask:0xf bank_mask:0xf
	v_fmac_f32_dpp v241, v101, v161 row_shr:1 row_mask:0xf bank_mask:0xf
	v_fmac_f32_dpp v238, v114, v158 row_shl:15 row_mask:0xf bank_mask:0xf
	v_fmac_f32_dpp v239, v115, v159 row_shl:15 row_mask:0xf bank_mask:0xf
	v_fmac_f32_dpp v240, v116, v160 row_shl:15 row_mask:0xf bank_mask:0xf
	v_fmac_f32_dpp v241, v117, v161 row_shl:15 row_mask:0xf bank_mask:0xf
	v_fmac_f32_dpp v238, v98, v166 row_shl:1 row_mask:0xf bank_mask:0xf
	v_fmac_f32_dpp v239, v99, v167 row_shl:1 row_mask:0xf bank_mask:0xf
	v_fmac_f32_dpp v240, v100, v168 row_shl:1 row_mask:0xf bank_mask:0xf
	v_fmac_f32_dpp v241, v101, v169 row_shl:1 row_mask:0xf bank_mask:0xf
	v_mul_f32_e32 v242, 0xbfb8aa3b, v226
	v_mul_f32_e32 v243, 0xbfb8aa3b, v227
	v_mul_f32_e32 v244, 0xbfb8aa3b, v228
	v_mul_f32_e32 v245, 0xbfb8aa3b, v229
	v_mul_f32_e32 v246, 0xbfb8aa3b, v230
	v_mul_f32_e32 v247, 0xbfb8aa3b, v231
	v_mul_f32_e32 v248, 0xbfb8aa3b, v232
	v_mul_f32_e32 v249, 0xbfb8aa3b, v233
	v_exp_f32_e32 v242, v242
	v_exp_f32_e32 v243, v243
	v_exp_f32_e32 v244, v244
	v_exp_f32_e32 v245, v245
	v_exp_f32_e32 v246, v246
	v_exp_f32_e32 v247, v247
	v_exp_f32_e32 v248, v248
	v_exp_f32_e32 v249, v249
	v_add_f32_e32 v242, 1.0, v242
	v_add_f32_e32 v243, 1.0, v243
	v_add_f32_e32 v244, 1.0, v244
	v_add_f32_e32 v245, 1.0, v245
	v_add_f32_e32 v246, 1.0, v246
	v_add_f32_e32 v247, 1.0, v247
	v_add_f32_e32 v248, 1.0, v248
	v_add_f32_e32 v249, 1.0, v249
	v_rcp_f32_e32 v242, v242
	v_rcp_f32_e32 v243, v243
	v_rcp_f32_e32 v244, v244
	v_rcp_f32_e32 v245, v245
	v_rcp_f32_e32 v246, v246
	v_rcp_f32_e32 v247, v247
	v_rcp_f32_e32 v248, v248
	v_rcp_f32_e32 v249, v249
	v_mul_f32_e32 v242, v226, v242
	v_mul_f32_e32 v243, v227, v243
	v_mul_f32_e32 v244, v228, v244
	v_mul_f32_e32 v245, v229, v245
	v_mul_f32_e32 v246, v230, v246
	v_mul_f32_e32 v247, v231, v247
	v_mul_f32_e32 v248, v232, v248
	v_mul_f32_e32 v249, v233, v249
	v_mul_f32_e32 v174, v174, v242
; __device__ __forceinline__ unsigned cvt_pk_bf16(float lo, float hi) { unsigned r; asm volatile("v_cvt_pk_bf16_f32 %0, %1, %2" : "=v"(r) : "v"(lo), "v"(hi)); return r; }
;     __device__ __forceinline__ void operator()(const f32x4 (&acc)[2][2][4][2], const Unit& u, int wr, int wc, int fr_in, int fq_in) const {
;     ...
;                         const f32x4 c = (k0 * xp + k1 * xv) + (k2 * xn + bb);
;                         if (pass == 0) o[m] = c;
;                         else { f32x4 e;
; #pragma unroll
;                             for (int j = 0; j < 4; ++j) e[j] = __builtin_amdgcn_rcpf(1.0f + __builtin_amdgcn_exp2f(c[j] * -1.4426950408889634f));
;                             o[m] = o[m] * (c * e); }
;                         up_prev = up_cur; dn_cur = dn_next; }
;                 }
;                 if (n == 0) {
; #pragma unroll
;                     for (int m = 0; m < 4; ++m) { wlo[m].x = cvt_pk_bf16(o[m][0], o[m][1]); wlo[m].y = cvt_pk_bf16(o[m][2], o[m][3]); }
;                 } else {
; #pragma unroll
;                     for (int m = 0; m < 4; ++m) { u32x4 w; w.x = wlo[m].x; w.y = wlo[m].y; w.z = cvt_pk_bf16(o[m][0], o[m][1]); w.w = cvt_pk_bf16(o[m][2], o[m][3]);
;                         *(u32x4*)(base + off0 + (unsigned)(ai * HALF + m * 16) * (DFF * 2u)) = w; }
;                 }
;                 if (fr < 2 || fr >= 14) { const int k = fr < 2 ? fr : fr - 12;
;                     const f32x4 xv = fr < 2 ? acc[ai][0][0][n] : acc[ai][0][3][n], yv = fr < 2 ? acc[ai][1][0][n] : acc[ai][1][3][n];
;                     char* sp = sbase + (size_t)((2 * ai + wr) * 4 + k) * (DFF2 * 2) + (size_t)ch * 2;
;                     u32x2 a, b; a.x = cvt_pk_bf16(xv[0], xv[1]); a.y = cvt_pk_bf16(xv[2], xv[3]); b.x = cvt_pk_bf16(yv[0], yv[1]); b.y = cvt_pk_bf16(yv[2], yv[3]);
;                     *(u32x2*)sp = a; *(u32x2*)(sp + DFF * 2) = b; }
	v_mul_f32_e32 v175, v175, v243
	v_mul_f32_e32 v176, v176, v244
	v_mul_f32_e32 v177, v177, v245
	v_mul_f32_e32 v178, v178, v246
	v_mul_f32_e32 v179, v179, v247
	v_mul_f32_e32 v180, v180, v248
	v_mul_f32_e32 v181, v181, v249
	v_mul_f32_e32 v242, 0xbfb8aa3b, v234
	v_mul_f32_e32 v243, 0xbfb8aa3b, v235
	v_mul_f32_e32 v244, 0xbfb8aa3b, v236
	v_mul_f32_e32 v245, 0xbfb8aa3b, v237
	v_mul_f32_e32 v246, 0xbfb8aa3b, v238
	v_mul_f32_e32 v247, 0xbfb8aa3b, v239
	v_mul_f32_e32 v248, 0xbfb8aa3b, v240
	v_mul_f32_e32 v249, 0xbfb8aa3b, v241
	v_exp_f32_e32 v242, v242
	v_exp_f32_e32 v243, v243
	v_exp_f32_e32 v244, v244
	v_exp_f32_e32 v245, v245
	v_exp_f32_e32 v246, v246
	v_exp_f32_e32 v247, v247
	v_exp_f32_e32 v248, v248
	v_exp_f32_e32 v249, v249
	v_add_f32_e32 v242, 1.0, v242
	v_add_f32_e32 v243, 1.0, v243
	v_add_f32_e32 v244, 1.0, v244
	v_add_f32_e32 v245, 1.0, v245
	v_add_f32_e32 v246, 1.0, v246
	v_add_f32_e32 v247, 1.0, v247
	v_add_f32_e32 v248, 1.0, v248
	v_add_f32_e32 v249, 1.0, v249
	v_rcp_f32_e32 v242, v242
	v_rcp_f32_e32 v243, v243
	v_rcp_f32_e32 v244, v244
	v_rcp_f32_e32 v245, v245
	v_rcp_f32_e32 v246, v246
	v_rcp_f32_e32 v247, v247
	v_rcp_f32_e32 v248, v248
	v_rcp_f32_e32 v249, v249
	v_mul_f32_e32 v242, v234, v242
	v_mul_f32_e32 v243, v235, v243
	v_mul_f32_e32 v244, v236, v244
	v_mul_f32_e32 v245, v237, v245
	v_mul_f32_e32 v246, v238, v246
	v_mul_f32_e32 v247, v239, v247
	v_mul_f32_e32 v248, v240, v248
	v_mul_f32_e32 v249, v241, v249
	v_mul_f32_e32 v186, v186, v242
	v_mul_f32_e32 v187, v187, v243
	v_mul_f32_e32 v188, v188, v244
	v_mul_f32_e32 v189, v189, v245
	v_mul_f32_e32 v190, v190, v246
	v_mul_f32_e32 v191, v191, v247
	v_mul_f32_e32 v192, v192, v248
	v_mul_f32_e32 v193, v193, v249
	v_cvt_pk_bf16_f32 v110, v174, v175
	v_cvt_pk_bf16_f32 v111, v176, v177
	v_cvt_pk_bf16_f32 v126, v178, v179
	v_cvt_pk_bf16_f32 v127, v180, v181
	v_cvt_pk_bf16_f32 v122, v186, v187
	v_cvt_pk_bf16_f32 v123, v188, v189
	v_cvt_pk_bf16_f32 v106, v190, v191
	v_cvt_pk_bf16_f32 v107, v192, v193
	v_cndmask_b32_e64 v202, v40, v44, s[12:13]
	v_cndmask_b32_e64 v203, v41, v45, s[12:13]
	v_cndmask_b32_e64 v204, v42, v46, s[12:13]
	v_cndmask_b32_e64 v205, v43, v47, s[12:13]
	v_cndmask_b32_e64 v206, v32, v36, s[12:13]
	v_cndmask_b32_e64 v207, v33, v37, s[12:13]
	v_cndmask_b32_e64 v208, v34, v38, s[12:13]
	v_cndmask_b32_e64 v209, v35, v39, s[12:13]
	v_cvt_pk_bf16_f32 v250, v202, v203
	v_cvt_pk_bf16_f32 v251, v204, v205
	v_cvt_pk_bf16_f32 v252, v206, v207
	v_cvt_pk_bf16_f32 v253, v208, v209
	s_add_u32 s10, s10, 0x16000
	s_addc_u32 s11, s11, 0
	s_mov_b64 s[42:43], exec
	s_and_b64 exec, exec, s[22:23]
	global_store_dwordx2 v195, v[250:251], s[10:11]
	global_store_dwordx2 v197, v[252:253], s[10:11]
	s_mov_b64 exec, s[42:43]
	v_fma_f32 v174, v134, v44, v142
	v_fma_f32 v175, v135, v45, v143
	v_fma_f32 v176, v136, v46, v144
	v_fma_f32 v177, v137, v47, v145
	v_fma_f32 v178, v134, v60, v142
	v_fma_f32 v179, v135, v61, v143
	v_fma_f32 v180, v136, v62, v144
	v_fma_f32 v181, v137, v63, v145
	v_fma_f32 v186, v134, v56, v142
	v_fma_f32 v187, v135, v57, v143
	v_fma_f32 v188, v136, v58, v144
	v_fma_f32 v189, v137, v59, v145
	v_fma_f32 v190, v134, v40, v142
	v_fma_f32 v191, v135, v41, v143
	v_fma_f32 v192, v136, v42, v144
	v_fma_f32 v193, v137, v43, v145
	v_fmac_f32_dpp v174, v44, v130 row_shr:1 row_mask:0xf bank_mask:0xf
	v_fmac_f32_dpp v175, v45, v131 row_shr:1 row_mask:0xf bank_mask:0xf
	v_fmac_f32_dpp v176, v46, v132 row_shr:1 row_mask:0xf bank_mask:0xf
	v_fmac_f32_dpp v177, v47, v133 row_shr:1 row_mask:0xf bank_mask:0xf
	v_fmac_f32_dpp v174, v44, v138 row_shl:1 row_mask:0xf bank_mask:0xf
	v_fmac_f32_dpp v175, v45, v139 row_shl:1 row_mask:0xf bank_mask:0xf
	v_fmac_f32_dpp v176, v46, v140 row_shl:1 row_mask:0xf bank_mask:0xf
	v_fmac_f32_dpp v177, v47, v141 row_shl:1 row_mask:0xf bank_mask:0xf
	v_fmac_f32_dpp v174, v60, v138 row_shr:15 row_mask:0xf bank_mask:0xf
	v_fmac_f32_dpp v175, v61, v139 row_shr:15 row_mask:0xf bank_mask:0xf
	v_fmac_f32_dpp v176, v62, v140 row_shr:15 row_mask:0xf bank_mask:0xf
	v_fmac_f32_dpp v177, v63, v141 row_shr:15 row_mask:0xf bank_mask:0xf
	v_fmac_f32_dpp v178, v60, v130 row_shr:1 row_mask:0xf bank_mask:0xf
	v_fmac_f32_dpp v179, v61, v131 row_shr:1 row_mask:0xf bank_mask:0xf
	v_fmac_f32_dpp v180, v62, v132 row_shr:1 row_mask:0xf bank_mask:0xf
	v_fmac_f32_dpp v181, v63, v133 row_shr:1 row_mask:0xf bank_mask:0xf
	v_fmac_f32_dpp v178, v44, v130 row_shl:15 row_mask:0xf bank_mask:0xf
	v_fmac_f32_dpp v179, v45, v131 row_shl:15 row_mask:0xf bank_mask:0xf
	v_fmac_f32_dpp v180, v46, v132 row_shl:15 row_mask:0xf bank_mask:0xf
	v_fmac_f32_dpp v181, v47, v133 row_shl:15 row_mask:0xf bank_mask:0xf
	v_fmac_f32_dpp v178, v60, v138 row_shl:1 row_mask:0xf bank_mask:0xf
	v_fmac_f32_dpp v179, v61, v139 row_shl:1 row_mask:0xf bank_mask:0xf
	v_fmac_f32_dpp v180, v62, v140 row_shl:1 row_mask:0xf bank_mask:0xf
	v_fmac_f32_dpp v181, v63, v141 row_shl:1 row_mask:0xf bank_mask:0xf
	v_fmac_f32_dpp v178, v56, v138 row_shr:15 row_mask:0xf bank_mask:0xf
	v_fmac_f32_dpp v179, v57, v139 row_shr:15 row_mask:0xf bank_mask:0xf
	v_fmac_f32_dpp v180, v58, v140 row_shr:15 row_mask:0xf bank_mask:0xf
	v_fmac_f32_dpp v181, v59, v141 row_shr:15 row_mask:0xf bank_mask:0xf
	v_fmac_f32_dpp v186, v56, v130 row_shr:1 row_mask:0xf bank_mask:0xf
	v_fmac_f32_dpp v187, v57, v131 row_shr:1 row_mask:0xf bank_mask:0xf
	v_fmac_f32_dpp v188, v58, v132 row_shr:1 row_mask:0xf bank_mask:0xf
	v_fmac_f32_dpp v189, v59, v133 row_shr:1 row_mask:0xf bank_mask:0xf
	v_fmac_f32_dpp v186, v60, v130 row_shl:15 row_mask:0xf bank_mask:0xf
	v_fmac_f32_dpp v187, v61, v131 row_shl:15 row_mask:0xf bank_mask:0xf
; #define DPP_UP(v) __int_as_float(__builtin_amdgcn_update_dpp(0, __float_as_int(v), 0x121, 0xf, 0xf, false))
; #define DPP_DN(v) __int_as_float(__builtin_amdgcn_update_dpp(0, __float_as_int(v), 0x12F, 0xf, 0xf, false))
;     __device__ __forceinline__ void operator()(const f32x4 (&acc)[2][2][4][2], const Unit& u, int wr, int wc, int fr_in, int fq_in) const {
;     ...
;                     const f32x4 k0 = *(const f32x4*)(fk + co + ch), k1 = *(const f32x4*)(fk + DFF2 + co + ch), k2 = *(const f32x4*)(fk + 2 * DFF2 + co + ch), bb = *(const f32x4*)(fb + co + ch);
;                     f32x4 up_prev = (f32x4){0.f, 0.f, 0.f, 0.f}, up_cur, dn_cur, dn_next;
; #pragma unroll
;                     for (int j = 0; j < 4; ++j) dn_cur[j] = DPP_DN(acc[ai][pass][0][n][j]);
; #pragma unroll
;                     for (int m = 0; m < 4; ++m) {
;                         const f32x4 xv = acc[ai][pass][m][n];
; #pragma unroll
;                         for (int j = 0; j < 4; ++j) { up_cur[j] = DPP_UP(xv[j]); dn_next[j] = (m < 3) ? DPP_DN(acc[ai][pass][m < 3 ? m + 1 : 3][n][j]) : 0.f; }
;                         const f32x4 xp = f0 ? up_prev : up_cur, xn = f15 ? dn_next : dn_cur;
;                         const f32x4 c = (k0 * xp + k1 * xv) + (k2 * xn + bb);
	v_fmac_f32_dpp v188, v62, v132 row_shl:15 row_mask:0xf bank_mask:0xf
	v_fmac_f32_dpp v189, v63, v133 row_shl:15 row_mask:0xf bank_mask:0xf
	v_fmac_f32_dpp v186, v56, v138 row_shl:1 row_mask:0xf bank_mask:0xf
	v_fmac_f32_dpp v187, v57, v139 row_shl:1 row_mask:0xf bank_mask:0xf
	v_fmac_f32_dpp v188, v58, v140 row_shl:1 row_mask:0xf bank_mask:0xf
	v_fmac_f32_dpp v189, v59, v141 row_shl:1 row_mask:0xf bank_mask:0xf
	v_fmac_f32_dpp v186, v40, v138 row_shr:15 row_mask:0xf bank_mask:0xf
	v_fmac_f32_dpp v187, v41, v139 row_shr:15 row_mask:0xf bank_mask:0xf
	v_fmac_f32_dpp v188, v42, v140 row_shr:15 row_mask:0xf bank_mask:0xf
	v_fmac_f32_dpp v189, v43, v141 row_shr:15 row_mask:0xf bank_mask:0xf
	v_fmac_f32_dpp v190, v40, v130 row_shr:1 row_mask:0xf bank_mask:0xf
	v_fmac_f32_dpp v191, v41, v131 row_shr:1 row_mask:0xf bank_mask:0xf
	v_fmac_f32_dpp v192, v42, v132 row_shr:1 row_mask:0xf bank_mask:0xf
	v_fmac_f32_dpp v193, v43, v133 row_shr:1 row_mask:0xf bank_mask:0xf
	v_fmac_f32_dpp v190, v56, v130 row_shl:15 row_mask:0xf bank_mask:0xf
	v_fmac_f32_dpp v191, v57, v131 row_shl:15 row_mask:0xf bank_mask:0xf
	v_fmac_f32_dpp v192, v58, v132 row_shl:15 row_mask:0xf bank_mask:0xf
	v_fmac_f32_dpp v193, v59, v133 row_shl:15 row_mask:0xf bank_mask:0xf
	v_fmac_f32_dpp v190, v40, v138 row_shl:1 row_mask:0xf bank_mask:0xf
	v_fmac_f32_dpp v191, v41, v139 row_shl:1 row_mask:0xf bank_mask:0xf
	v_fmac_f32_dpp v192, v42, v140 row_shl:1 row_mask:0xf bank_mask:0xf
	v_fmac_f32_dpp v193, v43, v141 row_shl:1 row_mask:0xf bank_mask:0xf
	v_fma_f32 v226, v162, v36, v170
	v_fma_f32 v227, v163, v37, v171
	v_fma_f32 v228, v164, v38, v172
	v_fma_f32 v229, v165, v39, v173
	v_fma_f32 v230, v162, v52, v170
	v_fma_f32 v231, v163, v53, v171
	v_fma_f32 v232, v164, v54, v172
	v_fma_f32 v233, v165, v55, v173
	v_fma_f32 v234, v162, v48, v170
	v_fma_f32 v235, v163, v49, v171
	v_fma_f32 v236, v164, v50, v172
	v_fma_f32 v237, v165, v51, v173
	v_fma_f32 v238, v162, v32, v170
	v_fma_f32 v239, v163, v33, v171
	v_fma_f32 v240, v164, v34, v172
	v_fma_f32 v241, v165, v35, v173
	v_fmac_f32_dpp v226, v36, v158 row_shr:1 row_mask:0xf bank_mask:0xf
	v_fmac_f32_dpp v227, v37, v159 row_shr:1 row_mask:0xf bank_mask:0xf
	v_fmac_f32_dpp v228, v38, v160 row_shr:1 row_mask:0xf bank_mask:0xf
	v_fmac_f32_dpp v229, v39, v161 row_shr:1 row_mask:0xf bank_mask:0xf
	v_fmac_f32_dpp v226, v36, v166 row_shl:1 row_mask:0xf bank_mask:0xf
	v_fmac_f32_dpp v227, v37, v167 row_shl:1 row_mask:0xf bank_mask:0xf
	v_fmac_f32_dpp v228, v38, v168 row_shl:1 row_mask:0xf bank_mask:0xf
	v_fmac_f32_dpp v229, v39, v169 row_shl:1 row_mask:0xf bank_mask:0xf
	v_fmac_f32_dpp v226, v52, v166 row_shr:15 row_mask:0xf bank_mask:0xf
	v_fmac_f32_dpp v227, v53, v167 row_shr:15 row_mask:0xf bank_mask:0xf
	v_fmac_f32_dpp v228, v54, v168 row_shr:15 row_mask:0xf bank_mask:0xf
	v_fmac_f32_dpp v229, v55, v169 row_shr:15 row_mask:0xf bank_mask:0xf
	v_fmac_f32_dpp v230, v52, v158 row_shr:1 row_mask:0xf bank_mask:0xf
	v_fmac_f32_dpp v231, v53, v159 row_shr:1 row_mask:0xf bank_mask:0xf
	v_fmac_f32_dpp v232, v54, v160 row_shr:1 row_mask:0xf bank_mask:0xf
	v_fmac_f32_dpp v233, v55, v161 row_shr:1 row_mask:0xf bank_mask:0xf
	v_fmac_f32_dpp v230, v36, v158 row_shl:15 row_mask:0xf bank_mask:0xf
	v_fmac_f32_dpp v231, v37, v159 row_shl:15 row_mask:0xf bank_mask:0xf
	v_fmac_f32_dpp v232, v38, v160 row_shl:15 row_mask:0xf bank_mask:0xf
	v_fmac_f32_dpp v233, v39, v161 row_shl:15 row_mask:0xf bank_mask:0xf
	v_fmac_f32_dpp v230, v52, v166 row_shl:1 row_mask:0xf bank_mask:0xf
	v_fmac_f32_dpp v231, v53, v167 row_shl:1 row_mask:0xf bank_mask:0xf
	v_fmac_f32_dpp v232, v54, v168 row_shl:1 row_mask:0xf bank_mask:0xf
	v_fmac_f32_dpp v233, v55, v169 row_shl:1 row_mask:0xf bank_mask:0xf
	v_fmac_f32_dpp v230, v48, v166 row_shr:15 row_mask:0xf bank_mask:0xf
	v_fmac_f32_dpp v231, v49, v167 row_shr:15 row_mask:0xf bank_mask:0xf
	v_fmac_f32_dpp v232, v50, v168 row_shr:15 row_mask:0xf bank_mask:0xf
	v_fmac_f32_dpp v233, v51, v169 row_shr:15 row_mask:0xf bank_mask:0xf
	v_fmac_f32_dpp v234, v48, v158 row_shr:1 row_mask:0xf bank_mask:0xf
	v_fmac_f32_dpp v235, v49, v159 row_shr:1 row_mask:0xf bank_mask:0xf
	v_fmac_f32_dpp v236, v50, v160 row_shr:1 row_mask:0xf bank_mask:0xf
	v_fmac_f32_dpp v237, v51, v161 row_shr:1 row_mask:0xf bank_mask:0xf
	v_fmac_f32_dpp v234, v52, v158 row_shl:15 row_mask:0xf bank_mask:0xf
	v_fmac_f32_dpp v235, v53, v159 row_shl:15 row_mask:0xf bank_mask:0xf
	v_fmac_f32_dpp v236, v54, v160 row_shl:15 row_mask:0xf bank_mask:0xf
	v_fmac_f32_dpp v237, v55, v161 row_shl:15 row_mask:0xf bank_mask:0xf
	v_fmac_f32_dpp v234, v48, v166 row_shl:1 row_mask:0xf bank_mask:0xf
	v_fmac_f32_dpp v235, v49, v167 row_shl:1 row_mask:0xf bank_mask:0xf
	v_fmac_f32_dpp v236, v50, v168 row_shl:1 row_mask:0xf bank_mask:0xf
	v_fmac_f32_dpp v237, v51, v169 row_shl:1 row_mask:0xf bank_mask:0xf
	v_fmac_f32_dpp v234, v32, v166 row_shr:15 row_mask:0xf bank_mask:0xf
	v_fmac_f32_dpp v235, v33, v167 row_shr:15 row_mask:0xf bank_mask:0xf
	v_fmac_f32_dpp v236, v34, v168 row_shr:15 row_mask:0xf bank_mask:0xf
	v_fmac_f32_dpp v237, v35, v169 row_shr:15 row_mask:0xf bank_mask:0xf
	v_fmac_f32_dpp v238, v32, v158 row_shr:1 row_mask:0xf bank_mask:0xf
	v_fmac_f32_dpp v239, v33, v159 row_shr:1 row_mask:0xf bank_mask:0xf
	v_fmac_f32_dpp v240, v34, v160 row_shr:1 row_mask:0xf bank_mask:0xf
	v_fmac_f32_dpp v241, v35, v161 row_shr:1 row_mask:0xf bank_mask:0xf
	v_fmac_f32_dpp v238, v48, v158 row_shl:15 row_mask:0xf bank_mask:0xf
	v_fmac_f32_dpp v239, v49, v159 row_shl:15 row_mask:0xf bank_mask:0xf
	v_fmac_f32_dpp v240, v50, v160 row_shl:15 row_mask:0xf bank_mask:0xf
	v_fmac_f32_dpp v241, v51, v161 row_shl:15 row_mask:0xf bank_mask:0xf
; __device__ __forceinline__ unsigned cvt_pk_bf16(float lo, float hi) { unsigned r; asm volatile("v_cvt_pk_bf16_f32 %0, %1, %2" : "=v"(r) : "v"(lo), "v"(hi)); return r; }
;     __device__ __forceinline__ void operator()(const f32x4 (&acc)[2][2][4][2], const Unit& u, int wr, int wc, int fr_in, int fq_in) const {
;     ...
;                         else { f32x4 e;
; #pragma unroll
;                             for (int j = 0; j < 4; ++j) e[j] = __builtin_amdgcn_rcpf(1.0f + __builtin_amdgcn_exp2f(c[j] * -1.4426950408889634f));
;                             o[m] = o[m] * (c * e); }
;                         up_prev = up_cur; dn_cur = dn_next; }
;                 }
;                 if (n == 0) {
; #pragma unroll
;                     for (int m = 0; m < 4; ++m) { wlo[m].x = cvt_pk_bf16(o[m][0], o[m][1]); wlo[m].y = cvt_pk_bf16(o[m][2], o[m][3]); }
;                 } else {
; #pragma unroll
;                     for (int m = 0; m < 4; ++m) { u32x4 w; w.x = wlo[m].x; w.y = wlo[m].y; w.z = cvt_pk_bf16(o[m][0], o[m][1]); w.w = cvt_pk_bf16(o[m][2], o[m][3]);
;                         *(u32x4*)(base + off0 + (unsigned)(ai * HALF + m * 16) * (DFF * 2u)) = w; }
;                 }
;                 if (fr < 2 || fr >= 14) { const int k = fr < 2 ? fr : fr - 12;
;                     const f32x4 xv = fr < 2 ? acc[ai][0][0][n] : acc[ai][0][3][n], yv = fr < 2 ? acc[ai][1][0][n] : acc[ai][1][3][n];
;                     char* sp = sbase + (size_t)((2 * ai + wr) * 4 + k) * (DFF2 * 2) + (size_t)ch * 2;
;                     u32x2 a, b; a.x = cvt_pk_bf16(xv[0], xv[1]); a.y = cvt_pk_bf16(xv[2], xv[3]); b.x = cvt_pk_bf16(yv[0], yv[1]); b.y = cvt_pk_bf16(yv[2], yv[3]);
;                     *(u32x2*)sp = a; *(u32x2*)(sp + DFF * 2) = b; }
	v_fmac_f32_dpp v238, v32, v166 row_shl:1 row_mask:0xf bank_mask:0xf
	v_fmac_f32_dpp v239, v33, v167 row_shl:1 row_mask:0xf bank_mask:0xf
	v_fmac_f32_dpp v240, v34, v168 row_shl:1 row_mask:0xf bank_mask:0xf
	v_fmac_f32_dpp v241, v35, v169 row_shl:1 row_mask:0xf bank_mask:0xf
	v_mul_f32_e32 v242, 0xbfb8aa3b, v226
	v_mul_f32_e32 v243, 0xbfb8aa3b, v227
	v_mul_f32_e32 v244, 0xbfb8aa3b, v228
	v_mul_f32_e32 v245, 0xbfb8aa3b, v229
	v_mul_f32_e32 v246, 0xbfb8aa3b, v230
	v_mul_f32_e32 v247, 0xbfb8aa3b, v231
	v_mul_f32_e32 v248, 0xbfb8aa3b, v232
	v_mul_f32_e32 v249, 0xbfb8aa3b, v233
	v_exp_f32_e32 v242, v242
	v_exp_f32_e32 v243, v243
	v_exp_f32_e32 v244, v244
	v_exp_f32_e32 v245, v245
	v_exp_f32_e32 v246, v246
	v_exp_f32_e32 v247, v247
	v_exp_f32_e32 v248, v248
	v_exp_f32_e32 v249, v249
	v_add_f32_e32 v242, 1.0, v242
	v_add_f32_e32 v243, 1.0, v243
	v_add_f32_e32 v244, 1.0, v244
	v_add_f32_e32 v245, 1.0, v245
	v_add_f32_e32 v246, 1.0, v246
	v_add_f32_e32 v247, 1.0, v247
	v_add_f32_e32 v248, 1.0, v248
	v_add_f32_e32 v249, 1.0, v249
	v_rcp_f32_e32 v242, v242
	v_rcp_f32_e32 v243, v243
	v_rcp_f32_e32 v244, v244
	v_rcp_f32_e32 v245, v245
	v_rcp_f32_e32 v246, v246
	v_rcp_f32_e32 v247, v247
	v_rcp_f32_e32 v248, v248
	v_rcp_f32_e32 v249, v249
	v_mul_f32_e32 v242, v226, v242
	v_mul_f32_e32 v243, v227, v243
	v_mul_f32_e32 v244, v228, v244
	v_mul_f32_e32 v245, v229, v245
	v_mul_f32_e32 v246, v230, v246
	v_mul_f32_e32 v247, v231, v247
	v_mul_f32_e32 v248, v232, v248
	v_mul_f32_e32 v249, v233, v249
	v_mul_f32_e32 v174, v174, v242
	v_mul_f32_e32 v175, v175, v243
	v_mul_f32_e32 v176, v176, v244
	v_mul_f32_e32 v177, v177, v245
	v_mul_f32_e32 v178, v178, v246
	v_mul_f32_e32 v179, v179, v247
	v_mul_f32_e32 v180, v180, v248
	v_mul_f32_e32 v181, v181, v249
	v_mul_f32_e32 v242, 0xbfb8aa3b, v234
	v_mul_f32_e32 v243, 0xbfb8aa3b, v235
	v_mul_f32_e32 v244, 0xbfb8aa3b, v236
	v_mul_f32_e32 v245, 0xbfb8aa3b, v237
	v_mul_f32_e32 v246, 0xbfb8aa3b, v238
	v_mul_f32_e32 v247, 0xbfb8aa3b, v239
	v_mul_f32_e32 v248, 0xbfb8aa3b, v240
	v_mul_f32_e32 v249, 0xbfb8aa3b, v241
	v_exp_f32_e32 v242, v242
	v_exp_f32_e32 v243, v243
	v_exp_f32_e32 v244, v244
	v_exp_f32_e32 v245, v245
	v_exp_f32_e32 v246, v246
	v_exp_f32_e32 v247, v247
	v_exp_f32_e32 v248, v248
	v_exp_f32_e32 v249, v249
	v_add_f32_e32 v242, 1.0, v242
	v_add_f32_e32 v243, 1.0, v243
	v_add_f32_e32 v244, 1.0, v244
	v_add_f32_e32 v245, 1.0, v245
	v_add_f32_e32 v246, 1.0, v246
	v_add_f32_e32 v247, 1.0, v247
	v_add_f32_e32 v248, 1.0, v248
	v_add_f32_e32 v249, 1.0, v249
	v_rcp_f32_e32 v242, v242
	v_rcp_f32_e32 v243, v243
	v_rcp_f32_e32 v244, v244
	v_rcp_f32_e32 v245, v245
	v_rcp_f32_e32 v246, v246
	v_rcp_f32_e32 v247, v247
	v_rcp_f32_e32 v248, v248
	v_rcp_f32_e32 v249, v249
	v_mul_f32_e32 v242, v234, v242
	v_mul_f32_e32 v243, v235, v243
	v_mul_f32_e32 v244, v236, v244
	v_mul_f32_e32 v245, v237, v245
	v_mul_f32_e32 v246, v238, v246
	v_mul_f32_e32 v247, v239, v247
	v_mul_f32_e32 v248, v240, v248
	v_mul_f32_e32 v249, v241, v249
	v_mul_f32_e32 v186, v186, v242
	v_mul_f32_e32 v187, v187, v243
	v_mul_f32_e32 v188, v188, v244
	v_mul_f32_e32 v189, v189, v245
	v_mul_f32_e32 v190, v190, v246
	v_mul_f32_e32 v191, v191, v247
	v_mul_f32_e32 v192, v192, v248
	v_mul_f32_e32 v193, v193, v249
	v_cvt_pk_bf16_f32 v44, v174, v175
	v_cvt_pk_bf16_f32 v45, v176, v177
	v_cvt_pk_bf16_f32 v60, v178, v179
	v_cvt_pk_bf16_f32 v61, v180, v181
	v_cvt_pk_bf16_f32 v56, v186, v187
	v_cvt_pk_bf16_f32 v57, v188, v189
	v_cvt_pk_bf16_f32 v40, v190, v191
	v_cvt_pk_bf16_f32 v41, v192, v193
	ds_read_b128 v[130:133], v213 offset:512
	ds_read_b128 v[134:137], v213 offset:576
	ds_read_b128 v[138:141], v213 offset:640
	ds_read_b128 v[142:145], v213 offset:704
	ds_read_b128 v[158:161], v213 offset:768
	ds_read_b128 v[162:165], v213 offset:832
	ds_read_b128 v[166:169], v213 offset:896
	ds_read_b128 v[170:173], v213 offset:960
	v_cndmask_b32_e64 v202, v72, v76, s[12:13]
	v_cndmask_b32_e64 v203, v73, v77, s[12:13]
	v_cndmask_b32_e64 v204, v74, v78, s[12:13]
	v_cndmask_b32_e64 v205, v75, v79, s[12:13]
	v_cndmask_b32_e64 v206, v68, v64, s[12:13]
	v_cndmask_b32_e64 v207, v69, v65, s[12:13]
	v_cndmask_b32_e64 v208, v70, v66, s[12:13]
	v_cndmask_b32_e64 v209, v71, v67, s[12:13]
	v_cvt_pk_bf16_f32 v250, v202, v203
	v_cvt_pk_bf16_f32 v251, v204, v205
	v_cvt_pk_bf16_f32 v252, v206, v207
	v_cvt_pk_bf16_f32 v253, v208, v209
	s_sub_u32 s10, s10, 0x16000
	s_subb_u32 s11, s11, 0
	s_mov_b64 s[42:43], exec
	s_and_b64 exec, exec, s[22:23]
	global_store_dwordx2 v195, v[250:251], s[10:11] offset:8
	global_store_dwordx2 v197, v[252:253], s[10:11] offset:8
	s_mov_b64 exec, s[42:43]
	s_waitcnt lgkmcnt(0)
; #define DPP_UP(v) __int_as_float(__builtin_amdgcn_update_dpp(0, __float_as_int(v), 0x121, 0xf, 0xf, false))
; #define DPP_DN(v) __int_as_float(__builtin_amdgcn_update_dpp(0, __float_as_int(v), 0x12F, 0xf, 0xf, false))
;     __device__ __forceinline__ void operator()(const f32x4 (&acc)[2][2][4][2], const Unit& u, int wr, int wc, int fr_in, int fq_in) const {
;     ...
;                     const f32x4 k0 = *(const f32x4*)(fk + co + ch), k1 = *(const f32x4*)(fk + DFF2 + co + ch), k2 = *(const f32x4*)(fk + 2 * DFF2 + co + ch), bb = *(const f32x4*)(fb + co + ch);
;                     f32x4 up_prev = (f32x4){0.f, 0.f, 0.f, 0.f}, up_cur, dn_cur, dn_next;
; #pragma unroll
;                     for (int j = 0; j < 4; ++j) dn_cur[j] = DPP_DN(acc[ai][pass][0][n][j]);
; #pragma unroll
;                     for (int m = 0; m < 4; ++m) {
;                         const f32x4 xv = acc[ai][pass][m][n];
; #pragma unroll
;                         for (int j = 0; j < 4; ++j) { up_cur[j] = DPP_UP(xv[j]); dn_next[j] = (m < 3) ? DPP_DN(acc[ai][pass][m < 3 ? m + 1 : 3][n][j]) : 0.f; }
;                         const f32x4 xp = f0 ? up_prev : up_cur, xn = f15 ? dn_next : dn_cur;
;                         const f32x4 c = (k0 * xp + k1 * xv) + (k2 * xn + bb);
;                         if (pass == 0) o[m] = c;
;                         else { f32x4 e;
; #pragma unroll
;                             for (int j = 0; j < 4; ++j) e[j] = __builtin_amdgcn_rcpf(1.0f + __builtin_amdgcn_exp2f(c[j] * -1.4426950408889634f));
;                             o[m] = o[m] * (c * e); }
;                         up_prev = up_cur; dn_cur = dn_next; }
	v_fma_f32 v174, v134, v76, v142
	v_fma_f32 v175, v135, v77, v143
	v_fma_f32 v176, v136, v78, v144
	v_fma_f32 v177, v137, v79, v145
	v_fma_f32 v178, v134, v92, v142
	v_fma_f32 v179, v135, v93, v143
	v_fma_f32 v180, v136, v94, v144
	v_fma_f32 v181, v137, v95, v145
	v_fma_f32 v186, v134, v88, v142
	v_fma_f32 v187, v135, v89, v143
	v_fma_f32 v188, v136, v90, v144
	v_fma_f32 v189, v137, v91, v145
	v_fma_f32 v190, v134, v72, v142
	v_fma_f32 v191, v135, v73, v143
	v_fma_f32 v192, v136, v74, v144
	v_fma_f32 v193, v137, v75, v145
	v_fmac_f32_dpp v174, v76, v130 row_shr:1 row_mask:0xf bank_mask:0xf
	v_fmac_f32_dpp v175, v77, v131 row_shr:1 row_mask:0xf bank_mask:0xf
	v_fmac_f32_dpp v176, v78, v132 row_shr:1 row_mask:0xf bank_mask:0xf
	v_fmac_f32_dpp v177, v79, v133 row_shr:1 row_mask:0xf bank_mask:0xf
	v_fmac_f32_dpp v174, v76, v138 row_shl:1 row_mask:0xf bank_mask:0xf
	v_fmac_f32_dpp v175, v77, v139 row_shl:1 row_mask:0xf bank_mask:0xf
	v_fmac_f32_dpp v176, v78, v140 row_shl:1 row_mask:0xf bank_mask:0xf
	v_fmac_f32_dpp v177, v79, v141 row_shl:1 row_mask:0xf bank_mask:0xf
	v_fmac_f32_dpp v174, v92, v138 row_shr:15 row_mask:0xf bank_mask:0xf
	v_fmac_f32_dpp v175, v93, v139 row_shr:15 row_mask:0xf bank_mask:0xf
	v_fmac_f32_dpp v176, v94, v140 row_shr:15 row_mask:0xf bank_mask:0xf
	v_fmac_f32_dpp v177, v95, v141 row_shr:15 row_mask:0xf bank_mask:0xf
	v_fmac_f32_dpp v178, v92, v130 row_shr:1 row_mask:0xf bank_mask:0xf
	v_fmac_f32_dpp v179, v93, v131 row_shr:1 row_mask:0xf bank_mask:0xf
	v_fmac_f32_dpp v180, v94, v132 row_shr:1 row_mask:0xf bank_mask:0xf
	v_fmac_f32_dpp v181, v95, v133 row_shr:1 row_mask:0xf bank_mask:0xf
	v_fmac_f32_dpp v178, v76, v130 row_shl:15 row_mask:0xf bank_mask:0xf
	v_fmac_f32_dpp v179, v77, v131 row_shl:15 row_mask:0xf bank_mask:0xf
	v_fmac_f32_dpp v180, v78, v132 row_shl:15 row_mask:0xf bank_mask:0xf
	v_fmac_f32_dpp v181, v79, v133 row_shl:15 row_mask:0xf bank_mask:0xf
	v_fmac_f32_dpp v178, v92, v138 row_shl:1 row_mask:0xf bank_mask:0xf
	v_fmac_f32_dpp v179, v93, v139 row_shl:1 row_mask:0xf bank_mask:0xf
	v_fmac_f32_dpp v180, v94, v140 row_shl:1 row_mask:0xf bank_mask:0xf
	v_fmac_f32_dpp v181, v95, v141 row_shl:1 row_mask:0xf bank_mask:0xf
	v_fmac_f32_dpp v178, v88, v138 row_shr:15 row_mask:0xf bank_mask:0xf
	v_fmac_f32_dpp v179, v89, v139 row_shr:15 row_mask:0xf bank_mask:0xf
	v_fmac_f32_dpp v180, v90, v140 row_shr:15 row_mask:0xf bank_mask:0xf
	v_fmac_f32_dpp v181, v91, v141 row_shr:15 row_mask:0xf bank_mask:0xf
	v_fmac_f32_dpp v186, v88, v130 row_shr:1 row_mask:0xf bank_mask:0xf
	v_fmac_f32_dpp v187, v89, v131 row_shr:1 row_mask:0xf bank_mask:0xf
	v_fmac_f32_dpp v188, v90, v132 row_shr:1 row_mask:0xf bank_mask:0xf
	v_fmac_f32_dpp v189, v91, v133 row_shr:1 row_mask:0xf bank_mask:0xf
	v_fmac_f32_dpp v186, v92, v130 row_shl:15 row_mask:0xf bank_mask:0xf
	v_fmac_f32_dpp v187, v93, v131 row_shl:15 row_mask:0xf bank_mask:0xf
	v_fmac_f32_dpp v188, v94, v132 row_shl:15 row_mask:0xf bank_mask:0xf
	v_fmac_f32_dpp v189, v95, v133 row_shl:15 row_mask:0xf bank_mask:0xf
	v_fmac_f32_dpp v186, v88, v138 row_shl:1 row_mask:0xf bank_mask:0xf
	v_fmac_f32_dpp v187, v89, v139 row_shl:1 row_mask:0xf bank_mask:0xf
	v_fmac_f32_dpp v188, v90, v140 row_shl:1 row_mask:0xf bank_mask:0xf
	v_fmac_f32_dpp v189, v91, v141 row_shl:1 row_mask:0xf bank_mask:0xf
	v_fmac_f32_dpp v186, v72, v138 row_shr:15 row_mask:0xf bank_mask:0xf
	v_fmac_f32_dpp v187, v73, v139 row_shr:15 row_mask:0xf bank_mask:0xf
	v_fmac_f32_dpp v188, v74, v140 row_shr:15 row_mask:0xf bank_mask:0xf
	v_fmac_f32_dpp v189, v75, v141 row_shr:15 row_mask:0xf bank_mask:0xf
	v_fmac_f32_dpp v190, v72, v130 row_shr:1 row_mask:0xf bank_mask:0xf
	v_fmac_f32_dpp v191, v73, v131 row_shr:1 row_mask:0xf bank_mask:0xf
	v_fmac_f32_dpp v192, v74, v132 row_shr:1 row_mask:0xf bank_mask:0xf
	v_fmac_f32_dpp v193, v75, v133 row_shr:1 row_mask:0xf bank_mask:0xf
	v_fmac_f32_dpp v190, v88, v130 row_shl:15 row_mask:0xf bank_mask:0xf
	v_fmac_f32_dpp v191, v89, v131 row_shl:15 row_mask:0xf bank_mask:0xf
	v_fmac_f32_dpp v192, v90, v132 row_shl:15 row_mask:0xf bank_mask:0xf
	v_fmac_f32_dpp v193, v91, v133 row_shl:15 row_mask:0xf bank_mask:0xf
	v_fmac_f32_dpp v190, v72, v138 row_shl:1 row_mask:0xf bank_mask:0xf
	v_fmac_f32_dpp v191, v73, v139 row_shl:1 row_mask:0xf bank_mask:0xf
	v_fmac_f32_dpp v192, v74, v140 row_shl:1 row_mask:0xf bank_mask:0xf
	v_fmac_f32_dpp v193, v75, v141 row_shl:1 row_mask:0xf bank_mask:0xf
	v_fma_f32 v226, v162, v64, v170
	v_fma_f32 v227, v163, v65, v171
	v_fma_f32 v228, v164, v66, v172
	v_fma_f32 v229, v165, v67, v173
	v_fma_f32 v230, v162, v84, v170
	v_fma_f32 v231, v163, v85, v171
	v_fma_f32 v232, v164, v86, v172
	v_fma_f32 v233, v165, v87, v173
	v_fma_f32 v234, v162, v80, v170
	v_fma_f32 v235, v163, v81, v171
	v_fma_f32 v236, v164, v82, v172
	v_fma_f32 v237, v165, v83, v173
	v_fma_f32 v238, v162, v68, v170
	v_fma_f32 v239, v163, v69, v171
	v_fma_f32 v240, v164, v70, v172
	v_fma_f32 v241, v165, v71, v173
	v_fmac_f32_dpp v226, v64, v158 row_shr:1 row_mask:0xf bank_mask:0xf
	v_fmac_f32_dpp v227, v65, v159 row_shr:1 row_mask:0xf bank_mask:0xf
	v_fmac_f32_dpp v228, v66, v160 row_shr:1 row_mask:0xf bank_mask:0xf
	v_fmac_f32_dpp v229, v67, v161 row_shr:1 row_mask:0xf bank_mask:0xf
	v_fmac_f32_dpp v226, v64, v166 row_shl:1 row_mask:0xf bank_mask:0xf
	v_fmac_f32_dpp v227, v65, v167 row_shl:1 row_mask:0xf bank_mask:0xf
	v_fmac_f32_dpp v228, v66, v168 row_shl:1 row_mask:0xf bank_mask:0xf
	v_fmac_f32_dpp v229, v67, v169 row_shl:1 row_mask:0xf bank_mask:0xf
	v_fmac_f32_dpp v226, v84, v166 row_shr:15 row_mask:0xf bank_mask:0xf
	v_fmac_f32_dpp v227, v85, v167 row_shr:15 row_mask:0xf bank_mask:0xf
; #define DPP_UP(v) __int_as_float(__builtin_amdgcn_update_dpp(0, __float_as_int(v), 0x121, 0xf, 0xf, false))
; #define DPP_DN(v) __int_as_float(__builtin_amdgcn_update_dpp(0, __float_as_int(v), 0x12F, 0xf, 0xf, false))
;     __device__ __forceinline__ void operator()(const f32x4 (&acc)[2][2][4][2], const Unit& u, int wr, int wc, int fr_in, int fq_in) const {
;     ...
;                         for (int j = 0; j < 4; ++j) { up_cur[j] = DPP_UP(xv[j]); dn_next[j] = (m < 3) ? DPP_DN(acc[ai][pass][m < 3 ? m + 1 : 3][n][j]) : 0.f; }
;                         const f32x4 xp = f0 ? up_prev : up_cur, xn = f15 ? dn_next : dn_cur;
;                         const f32x4 c = (k0 * xp + k1 * xv) + (k2 * xn + bb);
;                         if (pass == 0) o[m] = c;
;                         else { f32x4 e;
; #pragma unroll
;                             for (int j = 0; j < 4; ++j) e[j] = __builtin_amdgcn_rcpf(1.0f + __builtin_amdgcn_exp2f(c[j] * -1.4426950408889634f));
;                             o[m] = o[m] * (c * e); }
;                         up_prev = up_cur; dn_cur = dn_next; }
	v_fmac_f32_dpp v228, v86, v168 row_shr:15 row_mask:0xf bank_mask:0xf
	v_fmac_f32_dpp v229, v87, v169 row_shr:15 row_mask:0xf bank_mask:0xf
	v_fmac_f32_dpp v230, v84, v158 row_shr:1 row_mask:0xf bank_mask:0xf
	v_fmac_f32_dpp v231, v85, v159 row_shr:1 row_mask:0xf bank_mask:0xf
	v_fmac_f32_dpp v232, v86, v160 row_shr:1 row_mask:0xf bank_mask:0xf
	v_fmac_f32_dpp v233, v87, v161 row_shr:1 row_mask:0xf bank_mask:0xf
	v_fmac_f32_dpp v230, v64, v158 row_shl:15 row_mask:0xf bank_mask:0xf
	v_fmac_f32_dpp v231, v65, v159 row_shl:15 row_mask:0xf bank_mask:0xf
	v_fmac_f32_dpp v232, v66, v160 row_shl:15 row_mask:0xf bank_mask:0xf
	v_fmac_f32_dpp v233, v67, v161 row_shl:15 row_mask:0xf bank_mask:0xf
	v_fmac_f32_dpp v230, v84, v166 row_shl:1 row_mask:0xf bank_mask:0xf
	v_fmac_f32_dpp v231, v85, v167 row_shl:1 row_mask:0xf bank_mask:0xf
	v_fmac_f32_dpp v232, v86, v168 row_shl:1 row_mask:0xf bank_mask:0xf
	v_fmac_f32_dpp v233, v87, v169 row_shl:1 row_mask:0xf bank_mask:0xf
	v_fmac_f32_dpp v230, v80, v166 row_shr:15 row_mask:0xf bank_mask:0xf
	v_fmac_f32_dpp v231, v81, v167 row_shr:15 row_mask:0xf bank_mask:0xf
	v_fmac_f32_dpp v232, v82, v168 row_shr:15 row_mask:0xf bank_mask:0xf
	v_fmac_f32_dpp v233, v83, v169 row_shr:15 row_mask:0xf bank_mask:0xf
	v_fmac_f32_dpp v234, v80, v158 row_shr:1 row_mask:0xf bank_mask:0xf
	v_fmac_f32_dpp v235, v81, v159 row_shr:1 row_mask:0xf bank_mask:0xf
	v_fmac_f32_dpp v236, v82, v160 row_shr:1 row_mask:0xf bank_mask:0xf
	v_fmac_f32_dpp v237, v83, v161 row_shr:1 row_mask:0xf bank_mask:0xf
	v_fmac_f32_dpp v234, v84, v158 row_shl:15 row_mask:0xf bank_mask:0xf
	v_fmac_f32_dpp v235, v85, v159 row_shl:15 row_mask:0xf bank_mask:0xf
	v_fmac_f32_dpp v236, v86, v160 row_shl:15 row_mask:0xf bank_mask:0xf
	v_fmac_f32_dpp v237, v87, v161 row_shl:15 row_mask:0xf bank_mask:0xf
	v_fmac_f32_dpp v234, v80, v166 row_shl:1 row_mask:0xf bank_mask:0xf
	v_fmac_f32_dpp v235, v81, v167 row_shl:1 row_mask:0xf bank_mask:0xf
	v_fmac_f32_dpp v236, v82, v168 row_shl:1 row_mask:0xf bank_mask:0xf
	v_fmac_f32_dpp v237, v83, v169 row_shl:1 row_mask:0xf bank_mask:0xf
	v_fmac_f32_dpp v234, v68, v166 row_shr:15 row_mask:0xf bank_mask:0xf
	v_fmac_f32_dpp v235, v69, v167 row_shr:15 row_mask:0xf bank_mask:0xf
	v_fmac_f32_dpp v236, v70, v168 row_shr:15 row_mask:0xf bank_mask:0xf
	v_fmac_f32_dpp v237, v71, v169 row_shr:15 row_mask:0xf bank_mask:0xf
	v_fmac_f32_dpp v238, v68, v158 row_shr:1 row_mask:0xf bank_mask:0xf
	v_fmac_f32_dpp v239, v69, v159 row_shr:1 row_mask:0xf bank_mask:0xf
	v_fmac_f32_dpp v240, v70, v160 row_shr:1 row_mask:0xf bank_mask:0xf
	v_fmac_f32_dpp v241, v71, v161 row_shr:1 row_mask:0xf bank_mask:0xf
	v_fmac_f32_dpp v238, v80, v158 row_shl:15 row_mask:0xf bank_mask:0xf
	v_fmac_f32_dpp v239, v81, v159 row_shl:15 row_mask:0xf bank_mask:0xf
	v_fmac_f32_dpp v240, v82, v160 row_shl:15 row_mask:0xf bank_mask:0xf
	v_fmac_f32_dpp v241, v83, v161 row_shl:15 row_mask:0xf bank_mask:0xf
	v_fmac_f32_dpp v238, v68, v166 row_shl:1 row_mask:0xf bank_mask:0xf
	v_fmac_f32_dpp v239, v69, v167 row_shl:1 row_mask:0xf bank_mask:0xf
	v_fmac_f32_dpp v240, v70, v168 row_shl:1 row_mask:0xf bank_mask:0xf
	v_fmac_f32_dpp v241, v71, v169 row_shl:1 row_mask:0xf bank_mask:0xf
	v_mul_f32_e32 v242, 0xbfb8aa3b, v226
	v_mul_f32_e32 v243, 0xbfb8aa3b, v227
	v_mul_f32_e32 v244, 0xbfb8aa3b, v228
	v_mul_f32_e32 v245, 0xbfb8aa3b, v229
	v_mul_f32_e32 v246, 0xbfb8aa3b, v230
	v_mul_f32_e32 v247, 0xbfb8aa3b, v231
	v_mul_f32_e32 v248, 0xbfb8aa3b, v232
	v_mul_f32_e32 v249, 0xbfb8aa3b, v233
	v_exp_f32_e32 v242, v242
	v_exp_f32_e32 v243, v243
	v_exp_f32_e32 v244, v244
	v_exp_f32_e32 v245, v245
	v_exp_f32_e32 v246, v246
	v_exp_f32_e32 v247, v247
	v_exp_f32_e32 v248, v248
	v_exp_f32_e32 v249, v249
	v_add_f32_e32 v242, 1.0, v242
	v_add_f32_e32 v243, 1.0, v243
	v_add_f32_e32 v244, 1.0, v244
	v_add_f32_e32 v245, 1.0, v245
	v_add_f32_e32 v246, 1.0, v246
	v_add_f32_e32 v247, 1.0, v247
	v_add_f32_e32 v248, 1.0, v248
	v_add_f32_e32 v249, 1.0, v249
	v_rcp_f32_e32 v242, v242
	v_rcp_f32_e32 v243, v243
	v_rcp_f32_e32 v244, v244
	v_rcp_f32_e32 v245, v245
	v_rcp_f32_e32 v246, v246
	v_rcp_f32_e32 v247, v247
	v_rcp_f32_e32 v248, v248
	v_rcp_f32_e32 v249, v249
	v_mul_f32_e32 v242, v226, v242
	v_mul_f32_e32 v243, v227, v243
	v_mul_f32_e32 v244, v228, v244
	v_mul_f32_e32 v245, v229, v245
	v_mul_f32_e32 v246, v230, v246
	v_mul_f32_e32 v247, v231, v247
	v_mul_f32_e32 v248, v232, v248
	v_mul_f32_e32 v249, v233, v249
	v_mul_f32_e32 v174, v174, v242
	v_mul_f32_e32 v175, v175, v243
	v_mul_f32_e32 v176, v176, v244
	v_mul_f32_e32 v177, v177, v245
	v_mul_f32_e32 v178, v178, v246
	v_mul_f32_e32 v179, v179, v247
	v_mul_f32_e32 v180, v180, v248
	v_mul_f32_e32 v181, v181, v249
	v_mul_f32_e32 v242, 0xbfb8aa3b, v234
	v_mul_f32_e32 v243, 0xbfb8aa3b, v235
	v_mul_f32_e32 v244, 0xbfb8aa3b, v236
	v_mul_f32_e32 v245, 0xbfb8aa3b, v237
	v_mul_f32_e32 v246, 0xbfb8aa3b, v238
	v_mul_f32_e32 v247, 0xbfb8aa3b, v239
	v_mul_f32_e32 v248, 0xbfb8aa3b, v240
	v_mul_f32_e32 v249, 0xbfb8aa3b, v241
	v_exp_f32_e32 v242, v242
	v_exp_f32_e32 v243, v243
	v_exp_f32_e32 v244, v244
	v_exp_f32_e32 v245, v245
	v_exp_f32_e32 v246, v246
	v_exp_f32_e32 v247, v247
	v_exp_f32_e32 v248, v248
	v_exp_f32_e32 v249, v249
	v_add_f32_e32 v242, 1.0, v242
	v_add_f32_e32 v243, 1.0, v243
	v_add_f32_e32 v244, 1.0, v244
	v_add_f32_e32 v245, 1.0, v245
	v_add_f32_e32 v246, 1.0, v246
	v_add_f32_e32 v247, 1.0, v247
	v_add_f32_e32 v248, 1.0, v248
	v_add_f32_e32 v249, 1.0, v249
	v_rcp_f32_e32 v242, v242
	v_rcp_f32_e32 v243, v243
	v_rcp_f32_e32 v244, v244
	v_rcp_f32_e32 v245, v245
	v_rcp_f32_e32 v246, v246
	v_rcp_f32_e32 v247, v247
	v_rcp_f32_e32 v248, v248
	v_rcp_f32_e32 v249, v249
; __device__ __forceinline__ unsigned cvt_pk_bf16(float lo, float hi) { unsigned r; asm volatile("v_cvt_pk_bf16_f32 %0, %1, %2" : "=v"(r) : "v"(lo), "v"(hi)); return r; }
;     __device__ __forceinline__ void operator()(const f32x4 (&acc)[2][2][4][2], const Unit& u, int wr, int wc, int fr_in, int fq_in) const {
;     ...
;                             for (int j = 0; j < 4; ++j) e[j] = __builtin_amdgcn_rcpf(1.0f + __builtin_amdgcn_exp2f(c[j] * -1.4426950408889634f));
;                             o[m] = o[m] * (c * e); }
;                         up_prev = up_cur; dn_cur = dn_next; }
;                 }
;                 if (n == 0) {
; #pragma unroll
;                     for (int m = 0; m < 4; ++m) { wlo[m].x = cvt_pk_bf16(o[m][0], o[m][1]); wlo[m].y = cvt_pk_bf16(o[m][2], o[m][3]); }
;                 } else {
; #pragma unroll
;                     for (int m = 0; m < 4; ++m) { u32x4 w; w.x = wlo[m].x; w.y = wlo[m].y; w.z = cvt_pk_bf16(o[m][0], o[m][1]); w.w = cvt_pk_bf16(o[m][2], o[m][3]);
;                         *(u32x4*)(base + off0 + (unsigned)(ai * HALF + m * 16) * (DFF * 2u)) = w; }
;                 }
;                 if (fr < 2 || fr >= 14) { const int k = fr < 2 ? fr : fr - 12;
;                     const f32x4 xv = fr < 2 ? acc[ai][0][0][n] : acc[ai][0][3][n], yv = fr < 2 ? acc[ai][1][0][n] : acc[ai][1][3][n];
;                     char* sp = sbase + (size_t)((2 * ai + wr) * 4 + k) * (DFF2 * 2) + (size_t)ch * 2;
;                     u32x2 a, b; a.x = cvt_pk_bf16(xv[0], xv[1]); a.y = cvt_pk_bf16(xv[2], xv[3]); b.x = cvt_pk_bf16(yv[0], yv[1]); b.y = cvt_pk_bf16(yv[2], yv[3]);
;                     *(u32x2*)sp = a; *(u32x2*)(sp + DFF * 2) = b; }
	v_mul_f32_e32 v242, v234, v242
	v_mul_f32_e32 v243, v235, v243
	v_mul_f32_e32 v244, v236, v244
	v_mul_f32_e32 v245, v237, v245
	v_mul_f32_e32 v246, v238, v246
	v_mul_f32_e32 v247, v239, v247
	v_mul_f32_e32 v248, v240, v248
	v_mul_f32_e32 v249, v241, v249
	v_mul_f32_e32 v186, v186, v242
	v_mul_f32_e32 v187, v187, v243
	v_mul_f32_e32 v188, v188, v244
	v_mul_f32_e32 v189, v189, v245
	v_mul_f32_e32 v190, v190, v246
	v_mul_f32_e32 v191, v191, v247
	v_mul_f32_e32 v192, v192, v248
	v_mul_f32_e32 v193, v193, v249
	v_cvt_pk_bf16_f32 v112, v174, v175
	v_cvt_pk_bf16_f32 v113, v176, v177
	v_cvt_pk_bf16_f32 v128, v178, v179
	v_cvt_pk_bf16_f32 v129, v180, v181
	v_cvt_pk_bf16_f32 v124, v186, v187
	v_cvt_pk_bf16_f32 v125, v188, v189
	v_cvt_pk_bf16_f32 v108, v190, v191
	v_cvt_pk_bf16_f32 v109, v192, v193
	global_store_dwordx4 v194, v[110:113], s[6:7] nt
	s_add_u32 s0, s6, 0x16000
	s_addc_u32 s1, s7, 0
	global_store_dwordx4 v194, v[126:129], s[0:1] nt
	s_add_u32 s0, s6, 0x2c000
	s_addc_u32 s1, s7, 0
	global_store_dwordx4 v194, v[122:125], s[0:1] nt
	s_add_u32 s0, s6, 0x42000
	s_addc_u32 s1, s7, 0
	global_store_dwordx4 v194, v[106:109], s[0:1] nt
	v_cndmask_b32_e64 v202, v4, v0, s[12:13]
	v_cndmask_b32_e64 v203, v5, v1, s[12:13]
	v_cndmask_b32_e64 v204, v6, v2, s[12:13]
	v_cndmask_b32_e64 v205, v7, v3, s[12:13]
	v_cndmask_b32_e64 v206, v12, v8, s[12:13]
	v_cndmask_b32_e64 v207, v13, v9, s[12:13]
	v_cndmask_b32_e64 v208, v14, v10, s[12:13]
	v_cndmask_b32_e64 v209, v15, v11, s[12:13]
	v_cvt_pk_bf16_f32 v250, v202, v203
	v_cvt_pk_bf16_f32 v251, v204, v205
	v_cvt_pk_bf16_f32 v252, v206, v207
	v_cvt_pk_bf16_f32 v253, v208, v209
	s_add_u32 s10, s10, 0x16000
	s_addc_u32 s11, s11, 0
	s_mov_b64 s[42:43], exec
	s_and_b64 exec, exec, s[22:23]
	global_store_dwordx2 v195, v[250:251], s[10:11] offset:8
	global_store_dwordx2 v197, v[252:253], s[10:11] offset:8
	s_mov_b64 exec, s[42:43]
	v_fma_f32 v174, v134, v0, v142
	v_fma_f32 v175, v135, v1, v143
	v_fma_f32 v176, v136, v2, v144
	v_fma_f32 v177, v137, v3, v145
	v_fma_f32 v178, v134, v28, v142
	v_fma_f32 v179, v135, v29, v143
	v_fma_f32 v180, v136, v30, v144
	v_fma_f32 v181, v137, v31, v145
	v_fma_f32 v186, v134, v24, v142
	v_fma_f32 v187, v135, v25, v143
	v_fma_f32 v188, v136, v26, v144
	v_fma_f32 v189, v137, v27, v145
	v_fma_f32 v190, v134, v4, v142
	v_fma_f32 v191, v135, v5, v143
	v_fma_f32 v192, v136, v6, v144
	v_fma_f32 v193, v137, v7, v145
	v_fmac_f32_dpp v174, v0, v130 row_shr:1 row_mask:0xf bank_mask:0xf
	v_fmac_f32_dpp v175, v1, v131 row_shr:1 row_mask:0xf bank_mask:0xf
	v_fmac_f32_dpp v176, v2, v132 row_shr:1 row_mask:0xf bank_mask:0xf
	v_fmac_f32_dpp v177, v3, v133 row_shr:1 row_mask:0xf bank_mask:0xf
	v_fmac_f32_dpp v174, v0, v138 row_shl:1 row_mask:0xf bank_mask:0xf
	v_fmac_f32_dpp v175, v1, v139 row_shl:1 row_mask:0xf bank_mask:0xf
	v_fmac_f32_dpp v176, v2, v140 row_shl:1 row_mask:0xf bank_mask:0xf
	v_fmac_f32_dpp v177, v3, v141 row_shl:1 row_mask:0xf bank_mask:0xf
	v_fmac_f32_dpp v174, v28, v138 row_shr:15 row_mask:0xf bank_mask:0xf
	v_fmac_f32_dpp v175, v29, v139 row_shr:15 row_mask:0xf bank_mask:0xf
	v_fmac_f32_dpp v176, v30, v140 row_shr:15 row_mask:0xf bank_mask:0xf
	v_fmac_f32_dpp v177, v31, v141 row_shr:15 row_mask:0xf bank_mask:0xf
	v_fmac_f32_dpp v178, v28, v130 row_shr:1 row_mask:0xf bank_mask:0xf
	v_fmac_f32_dpp v179, v29, v131 row_shr:1 row_mask:0xf bank_mask:0xf
	v_fmac_f32_dpp v180, v30, v132 row_shr:1 row_mask:0xf bank_mask:0xf
	v_fmac_f32_dpp v181, v31, v133 row_shr:1 row_mask:0xf bank_mask:0xf
	v_fmac_f32_dpp v178, v0, v130 row_shl:15 row_mask:0xf bank_mask:0xf
	v_fmac_f32_dpp v179, v1, v131 row_shl:15 row_mask:0xf bank_mask:0xf
	v_fmac_f32_dpp v180, v2, v132 row_shl:15 row_mask:0xf bank_mask:0xf
	v_fmac_f32_dpp v181, v3, v133 row_shl:15 row_mask:0xf bank_mask:0xf
	v_fmac_f32_dpp v178, v28, v138 row_shl:1 row_mask:0xf bank_mask:0xf
	v_fmac_f32_dpp v179, v29, v139 row_shl:1 row_mask:0xf bank_mask:0xf
	v_fmac_f32_dpp v180, v30, v140 row_shl:1 row_mask:0xf bank_mask:0xf
	v_fmac_f32_dpp v181, v31, v141 row_shl:1 row_mask:0xf bank_mask:0xf
	v_fmac_f32_dpp v178, v24, v138 row_shr:15 row_mask:0xf bank_mask:0xf
	v_fmac_f32_dpp v179, v25, v139 row_shr:15 row_mask:0xf bank_mask:0xf
	v_fmac_f32_dpp v180, v26, v140 row_shr:15 row_mask:0xf bank_mask:0xf
	v_fmac_f32_dpp v181, v27, v141 row_shr:15 row_mask:0xf bank_mask:0xf
	v_fmac_f32_dpp v186, v24, v130 row_shr:1 row_mask:0xf bank_mask:0xf
	v_fmac_f32_dpp v187, v25, v131 row_shr:1 row_mask:0xf bank_mask:0xf
	v_fmac_f32_dpp v188, v26, v132 row_shr:1 row_mask:0xf bank_mask:0xf
	v_fmac_f32_dpp v189, v27, v133 row_shr:1 row_mask:0xf bank_mask:0xf
	v_fmac_f32_dpp v186, v28, v130 row_shl:15 row_mask:0xf bank_mask:0xf
	v_fmac_f32_dpp v187, v29, v131 row_shl:15 row_mask:0xf bank_mask:0xf
	v_fmac_f32_dpp v188, v30, v132 row_shl:15 row_mask:0xf bank_mask:0xf
	v_fmac_f32_dpp v189, v31, v133 row_shl:15 row_mask:0xf bank_mask:0xf
	v_fmac_f32_dpp v186, v24, v138 row_shl:1 row_mask:0xf bank_mask:0xf
	v_fmac_f32_dpp v187, v25, v139 row_shl:1 row_mask:0xf bank_mask:0xf
	v_fmac_f32_dpp v188, v26, v140 row_shl:1 row_mask:0xf bank_mask:0xf
	v_fmac_f32_dpp v189, v27, v141 row_shl:1 row_mask:0xf bank_mask:0xf
	v_fmac_f32_dpp v186, v4, v138 row_shr:15 row_mask:0xf bank_mask:0xf
	v_fmac_f32_dpp v187, v5, v139 row_shr:15 row_mask:0xf bank_mask:0xf
	v_fmac_f32_dpp v188, v6, v140 row_shr:15 row_mask:0xf bank_mask:0xf
	v_fmac_f32_dpp v189, v7, v141 row_shr:15 row_mask:0xf bank_mask:0xf
	v_fmac_f32_dpp v190, v4, v130 row_shr:1 row_mask:0xf bank_mask:0xf
	v_fmac_f32_dpp v191, v5, v131 row_shr:1 row_mask:0xf bank_mask:0xf
	v_fmac_f32_dpp v192, v6, v132 row_shr:1 row_mask:0xf bank_mask:0xf
; #define DPP_UP(v) __int_as_float(__builtin_amdgcn_update_dpp(0, __float_as_int(v), 0x121, 0xf, 0xf, false))
; #define DPP_DN(v) __int_as_float(__builtin_amdgcn_update_dpp(0, __float_as_int(v), 0x12F, 0xf, 0xf, false))
;     __device__ __forceinline__ void operator()(const f32x4 (&acc)[2][2][4][2], const Unit& u, int wr, int wc, int fr_in, int fq_in) const {
;     ...
;                     const f32x4 k0 = *(const f32x4*)(fk + co + ch), k1 = *(const f32x4*)(fk + DFF2 + co + ch), k2 = *(const f32x4*)(fk + 2 * DFF2 + co + ch), bb = *(const f32x4*)(fb + co + ch);
;                     f32x4 up_prev = (f32x4){0.f, 0.f, 0.f, 0.f}, up_cur, dn_cur, dn_next;
; #pragma unroll
;                     for (int j = 0; j < 4; ++j) dn_cur[j] = DPP_DN(acc[ai][pass][0][n][j]);
; #pragma unroll
;                     for (int m = 0; m < 4; ++m) {
;                         const f32x4 xv = acc[ai][pass][m][n];
; #pragma unroll
;                         for (int j = 0; j < 4; ++j) { up_cur[j] = DPP_UP(xv[j]); dn_next[j] = (m < 3) ? DPP_DN(acc[ai][pass][m < 3 ? m + 1 : 3][n][j]) : 0.f; }
;                         const f32x4 xp = f0 ? up_prev : up_cur, xn = f15 ? dn_next : dn_cur;
;                         const f32x4 c = (k0 * xp + k1 * xv) + (k2 * xn + bb);
	v_fmac_f32_dpp v193, v7, v133 row_shr:1 row_mask:0xf bank_mask:0xf
	v_fmac_f32_dpp v190, v24, v130 row_shl:15 row_mask:0xf bank_mask:0xf
	v_fmac_f32_dpp v191, v25, v131 row_shl:15 row_mask:0xf bank_mask:0xf
	v_fmac_f32_dpp v192, v26, v132 row_shl:15 row_mask:0xf bank_mask:0xf
	v_fmac_f32_dpp v193, v27, v133 row_shl:15 row_mask:0xf bank_mask:0xf
	v_fmac_f32_dpp v190, v4, v138 row_shl:1 row_mask:0xf bank_mask:0xf
	v_fmac_f32_dpp v191, v5, v139 row_shl:1 row_mask:0xf bank_mask:0xf
	v_fmac_f32_dpp v192, v6, v140 row_shl:1 row_mask:0xf bank_mask:0xf
	v_fmac_f32_dpp v193, v7, v141 row_shl:1 row_mask:0xf bank_mask:0xf
	v_fma_f32 v226, v162, v8, v170
	v_fma_f32 v227, v163, v9, v171
	v_fma_f32 v228, v164, v10, v172
	v_fma_f32 v229, v165, v11, v173
	v_fma_f32 v230, v162, v20, v170
	v_fma_f32 v231, v163, v21, v171
	v_fma_f32 v232, v164, v22, v172
	v_fma_f32 v233, v165, v23, v173
	v_fma_f32 v234, v162, v16, v170
	v_fma_f32 v235, v163, v17, v171
	v_fma_f32 v236, v164, v18, v172
	v_fma_f32 v237, v165, v19, v173
	v_fma_f32 v238, v162, v12, v170
	v_fma_f32 v239, v163, v13, v171
	v_fma_f32 v240, v164, v14, v172
	v_fma_f32 v241, v165, v15, v173
	v_fmac_f32_dpp v226, v8, v158 row_shr:1 row_mask:0xf bank_mask:0xf
	v_fmac_f32_dpp v227, v9, v159 row_shr:1 row_mask:0xf bank_mask:0xf
	v_fmac_f32_dpp v228, v10, v160 row_shr:1 row_mask:0xf bank_mask:0xf
	v_fmac_f32_dpp v229, v11, v161 row_shr:1 row_mask:0xf bank_mask:0xf
	v_fmac_f32_dpp v226, v8, v166 row_shl:1 row_mask:0xf bank_mask:0xf
	v_fmac_f32_dpp v227, v9, v167 row_shl:1 row_mask:0xf bank_mask:0xf
	v_fmac_f32_dpp v228, v10, v168 row_shl:1 row_mask:0xf bank_mask:0xf
	v_fmac_f32_dpp v229, v11, v169 row_shl:1 row_mask:0xf bank_mask:0xf
	v_fmac_f32_dpp v226, v20, v166 row_shr:15 row_mask:0xf bank_mask:0xf
	v_fmac_f32_dpp v227, v21, v167 row_shr:15 row_mask:0xf bank_mask:0xf
	v_fmac_f32_dpp v228, v22, v168 row_shr:15 row_mask:0xf bank_mask:0xf
	v_fmac_f32_dpp v229, v23, v169 row_shr:15 row_mask:0xf bank_mask:0xf
	v_fmac_f32_dpp v230, v20, v158 row_shr:1 row_mask:0xf bank_mask:0xf
	v_fmac_f32_dpp v231, v21, v159 row_shr:1 row_mask:0xf bank_mask:0xf
	v_fmac_f32_dpp v232, v22, v160 row_shr:1 row_mask:0xf bank_mask:0xf
	v_fmac_f32_dpp v233, v23, v161 row_shr:1 row_mask:0xf bank_mask:0xf
	v_fmac_f32_dpp v230, v8, v158 row_shl:15 row_mask:0xf bank_mask:0xf
	v_fmac_f32_dpp v231, v9, v159 row_shl:15 row_mask:0xf bank_mask:0xf
	v_fmac_f32_dpp v232, v10, v160 row_shl:15 row_mask:0xf bank_mask:0xf
	v_fmac_f32_dpp v233, v11, v161 row_shl:15 row_mask:0xf bank_mask:0xf
	v_fmac_f32_dpp v230, v20, v166 row_shl:1 row_mask:0xf bank_mask:0xf
	v_fmac_f32_dpp v231, v21, v167 row_shl:1 row_mask:0xf bank_mask:0xf
	v_fmac_f32_dpp v232, v22, v168 row_shl:1 row_mask:0xf bank_mask:0xf
	v_fmac_f32_dpp v233, v23, v169 row_shl:1 row_mask:0xf bank_mask:0xf
	v_fmac_f32_dpp v230, v16, v166 row_shr:15 row_mask:0xf bank_mask:0xf
	v_fmac_f32_dpp v231, v17, v167 row_shr:15 row_mask:0xf bank_mask:0xf
	v_fmac_f32_dpp v232, v18, v168 row_shr:15 row_mask:0xf bank_mask:0xf
	v_fmac_f32_dpp v233, v19, v169 row_shr:15 row_mask:0xf bank_mask:0xf
	v_fmac_f32_dpp v234, v16, v158 row_shr:1 row_mask:0xf bank_mask:0xf
	v_fmac_f32_dpp v235, v17, v159 row_shr:1 row_mask:0xf bank_mask:0xf
	v_fmac_f32_dpp v236, v18, v160 row_shr:1 row_mask:0xf bank_mask:0xf
	v_fmac_f32_dpp v237, v19, v161 row_shr:1 row_mask:0xf bank_mask:0xf
	v_fmac_f32_dpp v234, v20, v158 row_shl:15 row_mask:0xf bank_mask:0xf
	v_fmac_f32_dpp v235, v21, v159 row_shl:15 row_mask:0xf bank_mask:0xf
	v_fmac_f32_dpp v236, v22, v160 row_shl:15 row_mask:0xf bank_mask:0xf
	v_fmac_f32_dpp v237, v23, v161 row_shl:15 row_mask:0xf bank_mask:0xf
	v_fmac_f32_dpp v234, v16, v166 row_shl:1 row_mask:0xf bank_mask:0xf
	v_fmac_f32_dpp v235, v17, v167 row_shl:1 row_mask:0xf bank_mask:0xf
	v_fmac_f32_dpp v236, v18, v168 row_shl:1 row_mask:0xf bank_mask:0xf
	v_fmac_f32_dpp v237, v19, v169 row_shl:1 row_mask:0xf bank_mask:0xf
	v_fmac_f32_dpp v234, v12, v166 row_shr:15 row_mask:0xf bank_mask:0xf
	v_fmac_f32_dpp v235, v13, v167 row_shr:15 row_mask:0xf bank_mask:0xf
	v_fmac_f32_dpp v236, v14, v168 row_shr:15 row_mask:0xf bank_mask:0xf
	v_fmac_f32_dpp v237, v15, v169 row_shr:15 row_mask:0xf bank_mask:0xf
	v_fmac_f32_dpp v238, v12, v158 row_shr:1 row_mask:0xf bank_mask:0xf
	v_fmac_f32_dpp v239, v13, v159 row_shr:1 row_mask:0xf bank_mask:0xf
	v_fmac_f32_dpp v240, v14, v160 row_shr:1 row_mask:0xf bank_mask:0xf
	v_fmac_f32_dpp v241, v15, v161 row_shr:1 row_mask:0xf bank_mask:0xf
	v_fmac_f32_dpp v238, v16, v158 row_shl:15 row_mask:0xf bank_mask:0xf
	v_fmac_f32_dpp v239, v17, v159 row_shl:15 row_mask:0xf bank_mask:0xf
	v_fmac_f32_dpp v240, v18, v160 row_shl:15 row_mask:0xf bank_mask:0xf
	v_fmac_f32_dpp v241, v19, v161 row_shl:15 row_mask:0xf bank_mask:0xf
	v_fmac_f32_dpp v238, v12, v166 row_shl:1 row_mask:0xf bank_mask:0xf
; __device__ __forceinline__ unsigned cvt_pk_bf16(float lo, float hi) { unsigned r; asm volatile("v_cvt_pk_bf16_f32 %0, %1, %2" : "=v"(r) : "v"(lo), "v"(hi)); return r; }
;     __device__ __forceinline__ void operator()(const f32x4 (&acc)[2][2][4][2], const Unit& u, int wr, int wc, int fr_in, int fq_in) const {
;     ...
;                         else { f32x4 e;
; #pragma unroll
;                             for (int j = 0; j < 4; ++j) e[j] = __builtin_amdgcn_rcpf(1.0f + __builtin_amdgcn_exp2f(c[j] * -1.4426950408889634f));
;                             o[m] = o[m] * (c * e); }
;                         up_prev = up_cur; dn_cur = dn_next; }
;                 }
;                 if (n == 0) {
; #pragma unroll
;                     for (int m = 0; m < 4; ++m) { wlo[m].x = cvt_pk_bf16(o[m][0], o[m][1]); wlo[m].y = cvt_pk_bf16(o[m][2], o[m][3]); }
;                 } else {
; #pragma unroll
;                     for (int m = 0; m < 4; ++m) { u32x4 w; w.x = wlo[m].x; w.y = wlo[m].y; w.z = cvt_pk_bf16(o[m][0], o[m][1]); w.w = cvt_pk_bf16(o[m][2], o[m][3]);
;                         *(u32x4*)(base + off0 + (unsigned)(ai * HALF + m * 16) * (DFF * 2u)) = w; }
	v_fmac_f32_dpp v239, v13, v167 row_shl:1 row_mask:0xf bank_mask:0xf
	v_fmac_f32_dpp v240, v14, v168 row_shl:1 row_mask:0xf bank_mask:0xf
	v_fmac_f32_dpp v241, v15, v169 row_shl:1 row_mask:0xf bank_mask:0xf
	v_mul_f32_e32 v242, 0xbfb8aa3b, v226
	v_mul_f32_e32 v243, 0xbfb8aa3b, v227
	v_mul_f32_e32 v244, 0xbfb8aa3b, v228
	v_mul_f32_e32 v245, 0xbfb8aa3b, v229
	v_mul_f32_e32 v246, 0xbfb8aa3b, v230
	v_mul_f32_e32 v247, 0xbfb8aa3b, v231
	v_mul_f32_e32 v248, 0xbfb8aa3b, v232
	v_mul_f32_e32 v249, 0xbfb8aa3b, v233
	v_exp_f32_e32 v242, v242
	v_exp_f32_e32 v243, v243
	v_exp_f32_e32 v244, v244
	v_exp_f32_e32 v245, v245
	v_exp_f32_e32 v246, v246
	v_exp_f32_e32 v247, v247
	v_exp_f32_e32 v248, v248
	v_exp_f32_e32 v249, v249
	v_add_f32_e32 v242, 1.0, v242
	v_add_f32_e32 v243, 1.0, v243
	v_add_f32_e32 v244, 1.0, v244
	v_add_f32_e32 v245, 1.0, v245
	v_add_f32_e32 v246, 1.0, v246
	v_add_f32_e32 v247, 1.0, v247
	v_add_f32_e32 v248, 1.0, v248
	v_add_f32_e32 v249, 1.0, v249
	v_rcp_f32_e32 v242, v242
	v_rcp_f32_e32 v243, v243
	v_rcp_f32_e32 v244, v244
	v_rcp_f32_e32 v245, v245
	v_rcp_f32_e32 v246, v246
	v_rcp_f32_e32 v247, v247
	v_rcp_f32_e32 v248, v248
	v_rcp_f32_e32 v249, v249
	v_mul_f32_e32 v242, v226, v242
	v_mul_f32_e32 v243, v227, v243
	v_mul_f32_e32 v244, v228, v244
	v_mul_f32_e32 v245, v229, v245
	v_mul_f32_e32 v246, v230, v246
	v_mul_f32_e32 v247, v231, v247
	v_mul_f32_e32 v248, v232, v248
	v_mul_f32_e32 v249, v233, v249
	v_mul_f32_e32 v174, v174, v242
	v_mul_f32_e32 v175, v175, v243
	v_mul_f32_e32 v176, v176, v244
	v_mul_f32_e32 v177, v177, v245
	v_mul_f32_e32 v178, v178, v246
	v_mul_f32_e32 v179, v179, v247
	v_mul_f32_e32 v180, v180, v248
	v_mul_f32_e32 v181, v181, v249
	v_mul_f32_e32 v242, 0xbfb8aa3b, v234
	v_mul_f32_e32 v243, 0xbfb8aa3b, v235
	v_mul_f32_e32 v244, 0xbfb8aa3b, v236
	v_mul_f32_e32 v245, 0xbfb8aa3b, v237
	v_mul_f32_e32 v246, 0xbfb8aa3b, v238
	v_mul_f32_e32 v247, 0xbfb8aa3b, v239
	v_mul_f32_e32 v248, 0xbfb8aa3b, v240
	v_mul_f32_e32 v249, 0xbfb8aa3b, v241
	v_exp_f32_e32 v242, v242
	v_exp_f32_e32 v243, v243
	v_exp_f32_e32 v244, v244
	v_exp_f32_e32 v245, v245
	v_exp_f32_e32 v246, v246
	v_exp_f32_e32 v247, v247
	v_exp_f32_e32 v248, v248
	v_exp_f32_e32 v249, v249
	v_add_f32_e32 v242, 1.0, v242
	v_add_f32_e32 v243, 1.0, v243
	v_add_f32_e32 v244, 1.0, v244
	v_add_f32_e32 v245, 1.0, v245
	v_add_f32_e32 v246, 1.0, v246
	v_add_f32_e32 v247, 1.0, v247
	v_add_f32_e32 v248, 1.0, v248
	v_add_f32_e32 v249, 1.0, v249
	v_rcp_f32_e32 v242, v242
	v_rcp_f32_e32 v243, v243
	v_rcp_f32_e32 v244, v244
	v_rcp_f32_e32 v245, v245
	v_rcp_f32_e32 v246, v246
	v_rcp_f32_e32 v247, v247
	v_rcp_f32_e32 v248, v248
	v_rcp_f32_e32 v249, v249
	v_mul_f32_e32 v242, v234, v242
	v_mul_f32_e32 v243, v235, v243
	v_mul_f32_e32 v244, v236, v244
	v_mul_f32_e32 v245, v237, v245
	v_mul_f32_e32 v246, v238, v246
	v_mul_f32_e32 v247, v239, v247
	v_mul_f32_e32 v248, v240, v248
	v_mul_f32_e32 v249, v241, v249
	v_mul_f32_e32 v186, v186, v242
	v_mul_f32_e32 v187, v187, v243
	v_mul_f32_e32 v188, v188, v244
	v_mul_f32_e32 v189, v189, v245
	v_mul_f32_e32 v190, v190, v246
	v_mul_f32_e32 v191, v191, v247
	v_mul_f32_e32 v192, v192, v248
	v_mul_f32_e32 v193, v193, v249
	v_cvt_pk_bf16_f32 v46, v174, v175
	v_cvt_pk_bf16_f32 v47, v176, v177
	v_cvt_pk_bf16_f32 v62, v178, v179
	v_cvt_pk_bf16_f32 v63, v180, v181
	v_cvt_pk_bf16_f32 v58, v186, v187
	v_cvt_pk_bf16_f32 v59, v188, v189
	v_cvt_pk_bf16_f32 v42, v190, v191
	v_cvt_pk_bf16_f32 v43, v192, v193
	s_add_u32 s0, s6, 0xb0000
	s_addc_u32 s1, s7, 0
	global_store_dwordx4 v194, v[44:47], s[0:1] nt
	s_add_u32 s0, s6, 0xc6000
	s_addc_u32 s1, s7, 0
	global_store_dwordx4 v194, v[60:63], s[0:1] nt
	s_add_u32 s0, s6, 0xdc000
	s_addc_u32 s1, s7, 0
	global_store_dwordx4 v194, v[56:59], s[0:1] nt
	s_add_u32 s0, s6, 0xf2000
	s_addc_u32 s1, s7, 0
	global_store_dwordx4 v194, v[40:43], s[0:1] nt
	s_mov_b32 s101, 0
	s_cmp_eq_u64 s[4:5], 0
	s_cbranch_scc1 .Lp7_nopf
	v_and_b32_e32 v214, 63, v196
	v_bfe_u32 v130, v214, 2, 2
	v_bfe_u32 v131, v214, 4, 1
	v_lshrrev_b32_e32 v96, 5, v214
	v_and_b32_e32 v214, 3, v214
	s_lshl_b32 s0, s94, 7
	s_or_b32 s0, s0, s14
	v_lshl_add_u32 v214, v214, 3, s0
	v_lshl_add_u32 v214, v96, 2, v214
	v_lshlrev_b32_e32 v214, 2, v214
	v_mul_u32_u24_e32 v131, 0x2c00, v131
	v_add_u32_e32 v214, v214, v131
	v_cmp_eq_u32_e32 vcc, 3, v130
	v_mul_u32_u24_e32 v130, 0x5800, v130
	v_mov_b32_e32 v131, s53
	v_mov_b32_e32 v96, s54
	v_cndmask_b32_e64 v130, v130, 0, vcc
	v_add_u32_e32 v214, v214, v130
	v_mov_b32_e32 v130, s52
	v_cndmask_b32_e32 v130, v130, v96, vcc
	v_mov_b32_e32 v96, s55
	v_cndmask_b32_e32 v131, v131, v96, vcc
	v_add_co_u32_e32 v214, vcc, v130, v214
	s_nop 1
	v_addc_co_u32_e32 v215, vcc, 0, v131, vcc
	s_mov_b32 m0, s100
	s_nop 0
	global_load_lds_dwordx4 v[214:215], off
	s_movk_i32 s101, 0x7a9
